# v36 + accumulator zeroing removed in SchedH / merge x2 / P4 / P5a K-loops (peeled first iteration with C=0)
# speedup vs baseline: 1.0124x; 1.0022x over previous
.LBB0_537:
	s_or_b64 exec, exec, s[0:1]
	s_and_b64 s[0:1], s[36:37], exec
	s_cselect_b32 s28, 16, 0x1000
	s_add_u32 s64, s76, 0x13d00000
	s_addc_u32 s65, s77, 0
	s_bfe_u32 s68, s96, 0x20006
	s_mul_i32 s0, s68, 0x3700
	s_add_i32 s71, s0, 0
	s_and_b32 s0, s96, 0xffffff00
	s_lshr_b32 s74, s96, 8
	s_add_i32 s84, s0, 0
	s_lshl_b32 s11, s74, 5
	s_add_i32 s80, s84, 0x12600
	s_cmpk_lt_u32 s96, 0x540
	v_readlane_b32 s20, v255, 31
	s_cselect_b64 s[40:41], -1, 0
	s_add_i32 s12, s20, -4
	s_lshl_b32 s13, s12, 2
	s_lshl_b32 s22, s12, 10
	s_cmpk_lt_u32 s96, 0x440
	s_cselect_b64 s[42:43], -1, 0
	s_lshl_b32 s66, s20, 10
	s_cmpk_lt_u32 s96, 0x340
	s_cselect_b64 s[46:47], -1, 0
	s_add_i32 s14, s20, 4
	s_lshl_b32 s15, s14, 2
	s_lshl_b32 s23, s14, 10
	s_cmpk_lt_u32 s96, 0x240
	s_cselect_b64 s[48:49], -1, 0
	s_add_i32 s16, s20, 8
	s_lshl_b32 s17, s16, 2
	s_lshl_b32 s24, s16, 10
	s_cmp_eq_u32 s20, 4
	s_cselect_b64 s[50:51], -1, 0
	s_cmp_eq_u32 s20, 2
	s_mov_b32 s0, 0xfc00000
	s_cselect_b32 s38, s0, 0x13d00000
	s_add_u32 s8, s76, s6
	s_addc_u32 s9, s77, 0
	s_mul_i32 s0, s20, 0x2400
	s_add_i32 s1, 0, 0x1a900
	s_add_i32 s81, s1, s0
	s_lshl_b32 s0, s74, 7
	s_add_i32 s83, s0, 0
	s_add_i32 s82, s81, 0x2000
	s_add_i32 s83, s83, 0x14800
	s_add_i32 s84, s84, 0x12400
	s_lshl_b32 s29, s20, 5
	s_add_u32 s6, s64, s6
	s_addc_u32 s7, s65, 0
	s_lshl_b32 s85, s33, 10
	s_add_u32 s18, s76, 0x10000
	v_writelane_b32 v255, s96, 33
	s_addc_u32 s19, s77, 0
	v_lshl_or_b32 v11, s68, 4, v9
	v_writelane_b32 v255, s18, 34
	v_add_u32_e32 v25, 1, v11
	v_lshlrev_b32_e32 v27, 3, v38
	v_writelane_b32 v255, s19, 35
	v_lshlrev_b32_e32 v10, 7, v25
	v_and_b32_e32 v22, 8, v27
	s_add_i32 s0, 0, 0x1cd00
	s_add_i32 s18, 0, 0x1f100
	v_add3_u32 v91, s1, v10, v22
	v_add3_u32 v92, s0, v10, v22
	v_add3_u32 v93, s18, v10, v22
	v_lshlrev_b32_e32 v10, 8, v25
	s_add_i32 s19, 0, 0x23900
	v_add3_u32 v28, s19, v10, v22
	v_lshlrev_b32_e32 v10, 7, v11
	v_add3_u32 v94, s1, v10, v22
	v_add3_u32 v95, s0, v10, v22
	v_add3_u32 v96, s18, v10, v22
	v_lshlrev_b32_e32 v10, 8, v11
	v_add3_u32 v29, s19, v10, v22
	v_add_u32_e32 v10, 1, v89
	s_add_i32 s19, 0, 0x21500
	v_lshl_add_u32 v32, v10, 7, s19
	v_xor_b32_e32 v10, v10, v39
	v_lshlrev_b32_e32 v10, 4, v10
	v_and_b32_e32 v33, 0x70, v10
	v_lshlrev_b32_e32 v10, 7, v89
	v_add_u32_e32 v34, s19, v10
	s_add_i32 s19, 0, 0x12800
	s_cmp_lg_u32 s12, 16
	v_add_u32_e32 v36, s19, v10
	v_or_b32_e32 v10, s13, v38
	s_cselect_b64 vcc, -1, 0
	v_xor_b32_e32 v22, v89, v39
	v_cndmask_b32_e32 v98, 64, v10, vcc
	v_bitop3_b32 v10, v38, v39, s13 bitop3:0x36
	v_lshlrev_b32_e32 v22, 4, v22
	v_and_or_b32 v10, v10, 7, v41
	v_and_b32_e32 v35, 0x70, v22
	v_lshlrev_b32_e32 v22, 4, v10
	v_mov_b32_e32 v10, 0
	v_mov_b32_e32 v23, v10
	s_cmp_lg_u32 s20, 16
	v_lshl_add_u64 v[48:49], s[4:5], 0, v[22:23]
	v_or_b32_e32 v22, s3, v38
	s_cselect_b64 vcc, -1, 0
	v_cndmask_b32_e32 v99, 64, v22, vcc
	v_bitop3_b32 v22, v38, v39, s3 bitop3:0x36
	v_and_or_b32 v22, v22, 7, v41
	v_lshlrev_b32_e32 v22, 4, v22
	s_cmp_lg_u32 s14, 16
	v_lshl_add_u64 v[50:51], s[4:5], 0, v[22:23]
	v_or_b32_e32 v22, s15, v38
	s_cselect_b64 vcc, -1, 0
	v_cndmask_b32_e32 v100, 64, v22, vcc
	v_bitop3_b32 v22, v38, v39, s15 bitop3:0x36
	v_and_or_b32 v22, v22, 7, v41
	v_lshlrev_b32_e32 v22, 4, v22
	s_cmp_lg_u32 s16, 16
	v_lshl_add_u64 v[52:53], s[4:5], 0, v[22:23]
	v_or_b32_e32 v22, s17, v38
	s_cselect_b64 vcc, -1, 0
	v_cndmask_b32_e32 v101, 64, v22, vcc
	v_bitop3_b32 v22, v38, v39, s17 bitop3:0x36
	v_and_or_b32 v22, v22, 7, v41
	v_lshlrev_b32_e32 v22, 4, v22
	v_lshl_add_u64 v[54:55], s[4:5], 0, v[22:23]
	v_xor_b32_e32 v22, v38, v20
	s_movk_i32 s10, 0x3700
	v_or_b32_e32 v22, v22, v41
	v_lshlrev_b32_e32 v41, 5, v9
	v_lshrrev_b32_e32 v45, 7, v42
	v_cmp_gt_u32_e64 s[0:1], 16, v40
	v_or_b32_e32 v103, v27, v41
	v_lshl_add_u32 v104, v40, 2, s71
	v_add_u32_e32 v40, s71, v41
	v_lshrrev_b32_e32 v41, 2, v9
	v_mul_lo_u32 v45, v45, s10
	v_or_b32_e32 v41, v90, v41
	v_add_u32_e32 v67, 0, v45
	v_bfe_u32 v45, v42, 3, 4
	v_mul_u32_u24_e32 v41, 0x48, v41
	v_and_b32_e32 v21, 12, v21
	v_mul_u32_u24_e32 v45, 0x48, v45
	v_or_b32_e32 v24, s11, v90
	v_add_lshl_u32 v105, v21, v41, 1
	v_lshl_or_b32 v21, v89, 6, v8
	v_add_lshl_u32 v8, v45, v8, 1
	v_mov_b32_e32 v45, v10
	v_and_b32_e32 v26, 7, v25
	v_lshl_add_u64 v[60:61], s[6:7], 0, v[44:45]
	v_cmp_eq_u32_e64 s[6:7], 0, v42
	v_lshrrev_b32_e32 v42, 3, v24
	v_and_b32_e32 v62, 8, v42
	v_bitop3_b32 v63, v42, v26, 5 bitop3:0x6c
	v_or_b32_e32 v63, v63, v62
	v_lshlrev_b32_e32 v68, 4, v63
	v_add_u32_e32 v63, 64, v24
	v_bitop3_b32 v45, v42, v25, 7 bitop3:0x78
	v_lshrrev_b32_e32 v64, 3, v63
	v_xor_b32_e32 v69, v42, v20
	v_bitop3_b32 v42, v42, v20, 5 bitop3:0x6c
	v_and_b32_e32 v65, 8, v64
	v_or_b32_e32 v42, v42, v62
	v_bitop3_b32 v62, v64, v20, 5 bitop3:0x6c
	v_or_b32_e32 v62, v62, v65
	v_lshlrev_b32_e32 v108, 4, v69
	v_lshlrev_b32_e32 v69, 4, v62
	v_or_b32_e32 v62, 16, v24
	v_lshlrev_b32_e32 v22, 4, v22
	v_lshlrev_b32_e32 v71, 1, v63
	v_lshrrev_b32_e32 v63, 3, v62
	v_lshl_add_u64 v[56:57], s[4:5], 0, v[22:23]
	v_xor_b32_e32 v22, v88, v20
	v_bitop3_b32 v26, v64, v26, 5 bitop3:0x6c
	v_bitop3_b32 v64, v63, v25, 7 bitop3:0x78
	v_lshlrev_b32_e32 v22, 4, v22
	v_or_b32_e32 v26, v26, v65
	v_lshlrev_b32_e32 v111, 4, v64
	v_and_b32_e32 v64, 8, v63
	v_bitop3_b32 v65, v63, v25, 7 bitop3:0x28
	s_movk_i32 s18, 0x48
	v_lshl_add_u64 v[58:59], s[8:9], 0, v[22:23]
	v_or_b32_e32 v23, s11, v9
	v_or_b32_e32 v65, v65, v64
	v_mul_u32_u24_e32 v30, 0x48, v11
	v_mul_u32_u24_e32 v31, 0x48, v9
	v_lshlrev_b32_e32 v97, 2, v11
	v_or_b32_e32 v22, 16, v90
	v_lshlrev_b32_e32 v72, 4, v65
	v_add_u32_e32 v65, 0x50, v24
	v_mul_lo_u32 v23, v23, s18
	v_mad_u32_u24 v11, v11, s18, 32
	v_lshlrev_b32_e32 v70, 1, v24
	v_add_lshl_u32 v109, v24, v30, 1
	v_add_lshl_u32 v110, v24, v31, 1
	v_lshrrev_b32_e32 v73, 3, v65
	v_xor_b32_e32 v75, v63, v20
	v_bitop3_b32 v63, v63, v20, 7 bitop3:0x6c
	v_add_lshl_u32 v113, v62, v30, 1
	v_add_lshl_u32 v115, v30, v90, 1
	v_add_lshl_u32 v116, v22, v30, 1
	v_add_u32_e32 v30, 0x480, v23
	v_add_lshl_u32 v119, v11, v90, 1
	v_add_lshl_u32 v120, v11, v22, 1
	v_or_b32_e32 v11, 32, v90
	v_lshlrev_b32_e32 v123, 2, v24
	v_or_b32_e32 v24, 1, v90
	v_cmp_eq_u32_e32 vcc, v90, v9
	v_lshlrev_b32_e32 v106, 5, v20
	v_and_b32_e32 v74, 8, v73
	v_bitop3_b32 v25, v73, v25, 7 bitop3:0x28
	v_or_b32_e32 v63, v63, v64
	v_bitop3_b32 v20, v73, v20, 7 bitop3:0x6c
	v_lshlrev_b32_e32 v73, 1, v62
	v_add_lshl_u32 v114, v62, v31, 1
	v_add_lshl_u32 v118, v30, v90, 1
	v_add_lshl_u32 v122, v11, v30, 1
	v_lshlrev_b32_e32 v124, 2, v62
	v_or_b32_e32 v30, 2, v90
	v_cndmask_b32_e64 v62, 0, 1.0, vcc
	v_cmp_eq_u32_e32 vcc, v24, v9
	v_lshlrev_b32_e32 v112, 4, v75
	v_lshlrev_b32_e32 v75, 4, v63
	v_add_lshl_u32 v117, v90, v23, 1
	v_add_lshl_u32 v121, v11, v23, 1
	v_add_lshl_u32 v125, v90, v31, 1
	v_add_lshl_u32 v23, v11, v31, 1
	v_or_b32_e32 v31, 3, v90
	v_cndmask_b32_e64 v63, 0, 1.0, vcc
	v_cmp_eq_u32_e32 vcc, v30, v9
	v_cmp_eq_u32_e64 s[4:5], 0, v9
	v_mad_u32_u24 v37, v9, s18, 16
	v_cmp_lt_u32_e64 s[8:9], v90, v9
	v_cmp_gt_u32_e64 s[10:11], v90, v9
	v_cmp_lt_u32_e64 s[12:13], v24, v9
	v_cmp_lt_u32_e64 s[14:15], v30, v9
	v_cmp_gt_u32_e64 s[16:17], v30, v9
	v_cmp_lt_u32_e64 s[18:19], v31, v9
	v_cmp_gt_u32_e64 s[20:21], v31, v9
	v_cndmask_b32_e64 v64, 0, 1.0, vcc
	v_cmp_eq_u32_e32 vcc, v31, v9
	v_lshlrev_b32_e32 v9, 2, v9
	v_lshl_add_u32 v24, v38, 10, s97
	s_mov_b32 s3, 0xdc00
	v_add3_u32 v126, v24, v9, s3
	v_and_b32_e32 v9, 3, v39
	s_movk_i32 s25, 0x2400
	v_lshlrev_b32_e32 v43, 2, v21
	v_lshlrev_b32_e32 v21, 1, v21
	v_lshl_or_b32 v9, v9, 3, s29
	v_lshlrev_b32_e32 v24, 1, v41
	s_waitcnt lgkmcnt(0)
	s_barrier
	v_lshlrev_b32_e32 v66, 2, v89
	v_or_b32_e32 v25, v25, v74
	v_or_b32_e32 v20, v20, v74
	v_add3_u32 v128, v9, v24, s25
	v_mov_b32_e32 v9, 0x3540
	v_add_u32_e32 v151, v67, v8
	v_add_u32_e32 v8, 0, v21
	s_mov_b32 s39, 0
	v_and_b32_e32 v102, 48, v39
	v_lshlrev_b32_e32 v26, 4, v26
	v_lshlrev_b32_e32 v42, 4, v42
	v_lshlrev_b32_e32 v25, 4, v25
	v_lshlrev_b32_e32 v20, 4, v20
	v_lshlrev_b32_e32 v74, 1, v65
	v_add_lshl_u32 v22, v37, v90, 1
	v_add_lshl_u32 v11, v11, v37, 1
	v_writelane_b32 v255, s97, 32
	v_lshl_or_b32 v129, v38, 4, v9
	s_add_i32 s3, 0, 0x15c00
	s_add_i32 s88, s22, 0
	s_add_i32 s89, s23, 0
	s_add_i32 s90, s24, 0
	v_add_u32_e32 v9, 0, v66
	v_add_u32_e32 v152, 0x12800, v8
	v_mbcnt_lo_u32_b32 v8, -1, 0
	s_mov_b64 s[52:53], s[38:39]
	v_add_u32_e32 v107, s70, v89
	v_lshlrev_b32_e32 v45, 4, v45
	v_cndmask_b32_e64 v65, 0, 1.0, vcc
	v_add_u32_e32 v127, 0x2d00, v103
	v_writelane_b32 v255, s29, 44
	v_or_b32_e32 v130, 0x3500, v102
	v_add_u32_e32 v131, v28, v68
	v_add_u32_e32 v132, v28, v26
	v_add_u32_e32 v133, v29, v42
	v_add_u32_e32 v134, v29, v69
	v_add_u32_e32 v135, s3, v70
	v_add_u32_e32 v136, s3, v71
	s_mov_b32 s86, 0x4038aa3b
	s_add_i32 s67, 0, 0x10000
	v_add_u32_e32 v137, v28, v72
	v_add_u32_e32 v138, v28, v25
	v_add_u32_e32 v139, v29, v75
	v_add_u32_e32 v140, v29, v20
	v_add_u32_e32 v141, s3, v73
	v_add_u32_e32 v142, s3, v74
	v_add_u32_e32 v143, v32, v33
	v_add_u32_e32 v145, v34, v35
	s_mov_b32 s87, 0xbfb8aa3b
	v_add_u32_e32 v146, v36, v44
	s_add_i32 s88, s88, 0x23900
	s_add_i32 s89, s89, 0x23900
	s_add_i32 s90, s90, 0x23900
	s_add_i32 s91, 0, 0x27900
	s_add_i32 s92, s81, 0x400
	s_add_i32 s93, s81, 0x800
	s_add_i32 s94, s81, 0xc00
	s_add_i32 s95, s81, 0x1400
	s_add_i32 s96, s81, 0x1800
	s_add_i32 s97, s81, 0x1c00
	s_add_i32 s3, 0, 0x16100
	s_add_i32 s69, 0, 0x18500
	v_mov_b32_e32 v147, 0xbf92477c
	v_add_u32_e32 v148, v40, v27
	s_xor_b64 s[54:55], s[26:27], -1
	v_add_u32_e32 v149, 0, v43
	v_add_u32_e32 v150, 0x12400, v9
	v_mov_b32_e32 v153, 0x3a27c5ac
	v_mbcnt_hi_u32_b32 v144, -1, v8
	v_add_u32_e32 v154, s71, v22
	v_add_u32_e32 v155, s71, v23
	v_add_u32_e32 v156, s71, v11
	s_mov_b32 s33, s28
	s_mov_b32 s29, 0
	v_add_u32_e32 v211, v93, v45
	v_add_u32_e32 v233, s67, v119
	v_add_u32_e32 v210, v96, v108
	v_add_u32_e32 v224, s71, v114
	v_add_u32_e32 v228, s67, v116
	v_add_u32_e32 v232, s69, v118
	v_add_u32_e32 v214, s71, v110
	v_add_u32_e32 v223, s67, v113
	v_add_u32_e32 v212, v91, v45
	v_add_u32_e32 v213, s67, v109
	v_add_u32_e32 v239, 0x12600, v97
	v_add_u32_e32 v235, s3, v121
	v_add_u32_e32 v219, v93, v111
	v_add_u32_e32 v208, v94, v108
	v_add_u32_e32 v220, v91, v111
	v_xor_b32_e32 v243, 32, v144
	v_and_b32_e32 v241, 64, v144
	v_add_u32_e32 v21, 64, v241
	v_cmp_lt_i32_e32 vcc, v243, v21
	s_nop 1
	v_cndmask_b32_e32 v20, v144, v243, vcc
	v_lshlrev_b32_e32 v222, 2, v20
	v_xor_b32_e32 v242, 16, v144
	v_cmp_lt_i32_e32 vcc, v242, v21
	s_nop 1
	v_cndmask_b32_e32 v22, v144, v242, vcc
	v_lshlrev_b32_e32 v221, 2, v22
	v_add_u32_e32 v237, s3, v122
	v_add_u32_e32 v231, s3, v118
	v_add_u32_e32 v207, v92, v45
	v_or_b32_e32 v240, v102, v241
	v_add_u32_e32 v217, v95, v112
	v_add_u32_e32 v215, v92, v111
	v_add_u32_e32 v227, s67, v115
	v_add_u32_e32 v236, s69, v121
	v_add_u32_e32 v225, 0x15d80, v44
	v_add_u32_e32 v209, v95, v108
	v_add_u32_e32 v230, s69, v117
	v_add_u32_e32 v218, v96, v112
	v_add_u32_e32 v226, s83, v102
	v_add_u32_e32 v229, s3, v117
	v_add_u32_e32 v216, v94, v112
	v_add_u32_e32 v238, s69, v122
	v_add_u32_e32 v234, s67, v120
	v_mov_b32_e32 v252, 0
	s_waitcnt vmcnt(0)

.LBB0_641:
	v_and_b32_e32 v142, 15, v2
	v_and_b32_e32 v143, 48, v2
	v_lshlrev_b32_e32 v2, 2, v2
	s_lshl_b32 s14, s14, 21
	v_lshl_or_b32 v7, v142, 6, v143
	v_and_b32_e32 v2, 32, v2
	s_and_b32 s14, s14, 0x3800000
	s_lshl_b32 s15, s15, 19
	v_bitop3_b32 v8, v7, s52, v2 bitop3:0xde
	v_bitop3_b32 v145, v7, s53, v2 bitop3:0xde
	s_add_i32 s14, s14, s15
	v_lshlrev_b32_e32 v2, 14, v0
	s_add_u32 s40, s76, s14
	v_and_b32_e32 v2, 0xffff8000, v2
	s_addc_u32 s41, s77, 0
	v_lshl_add_u32 v1, v1, 11, v2
	v_and_b32_e32 v0, 1, v0
	v_lshl_or_b32 v0, v0, 6, v1
	s_add_u32 s14, s3, s14
	v_lshl_add_u32 v0, v3, 1, v0
	v_mov_b32_e32 v1, v129
	s_addc_u32 s15, s28, 0
	v_lshl_add_u64 v[136:137], s[14:15], 0, v[0:1]
	v_lshlrev_b32_e32 v0, 14, v4
	v_and_b32_e32 v0, 0xffff8000, v0
	v_lshl_add_u32 v0, v5, 11, v0
	v_and_b32_e32 v1, 1, v4
	v_lshl_or_b32 v0, v1, 6, v0
	s_waitcnt vmcnt(8)
	s_barrier
	s_waitcnt vmcnt(6)
	v_lshl_add_u32 v0, v6, 1, v0
	v_mov_b32_e32 v1, v129
	v_lshl_add_u64 v[138:139], s[14:15], 0, v[0:1]
	s_add_u32 s42, s29, s16
	s_addc_u32 s43, s33, 0
	s_mov_b32 s46, -2
	s_mov_b64 s[14:15], 0
	v_add_u32_e32 v146, 0, v8
	s_barrier
	s_add_u32 s16, s40, s14
	s_addc_u32 s17, s41, s15
	s_add_u32 s16, s16, 0x13d00100
	s_addc_u32 s17, s17, 0
	s_add_u32 s47, s42, s14
	s_addc_u32 s48, s43, s15
	s_cmpk_eq_i32 s14, 0x700
	s_cselect_b32 s19, s11, s17
	s_cselect_b32 s18, s10, s16
	v_add_u32_e32 v147, s67, v145
	s_cselect_b32 s17, s13, s48
	s_cselect_b32 s16, s12, s47
	s_add_i32 s47, 0, 0x14000
	ds_read_b128 v[148:151], v147
	ds_read_b128 v[152:155], v147 offset:1024
	ds_read_b128 v[156:159], v147 offset:2048
	ds_read_b128 v[160:163], v147 offset:3072
	v_add_u32_e32 v147, s47, v145
	ds_read_b128 v[164:167], v147
	ds_read_b128 v[168:171], v147 offset:1024
	ds_read_b128 v[172:175], v147 offset:2048
	ds_read_b128 v[176:179], v147 offset:3072
	v_lshl_add_u64 v[212:213], v[136:137], 0, s[14:15]
	s_add_i32 m0, s30, 0xc000
	ds_read_b128 v[180:183], v146
	ds_read_b128 v[184:187], v146 offset:1024
	ds_read_b128 v[188:191], v146 offset:2048
	ds_read_b128 v[192:195], v146 offset:3072
	ds_read_b128 v[196:199], v146 offset:4096
	ds_read_b128 v[200:203], v146 offset:5120
	ds_read_b128 v[204:207], v146 offset:6144
	ds_read_b128 v[208:211], v146 offset:7168
	global_load_lds_dwordx4 v[212:213], off
	v_lshl_add_u64 v[212:213], v[138:139], 0, s[14:15]
	s_add_i32 m0, s30, 0xe000
	s_nop 0
	global_load_lds_dwordx4 v[212:213], off
	s_waitcnt vmcnt(8)
	s_waitcnt lgkmcnt(0)
	s_barrier
	s_waitcnt lgkmcnt(0)
	v_mfma_f32_16x16x32_f16 v[124:127], v[148:151], v[180:183], 0
	v_mfma_f32_16x16x32_f16 v[120:123], v[156:159], v[180:183], 0
	v_mfma_f32_16x16x32_f16 v[108:111], v[148:151], v[188:191], 0
	v_mfma_f32_16x16x32_f16 v[104:107], v[156:159], v[188:191], 0
	v_mfma_f32_16x16x32_f16 v[92:95], v[148:151], v[196:199], 0
	v_mfma_f32_16x16x32_f16 v[88:91], v[156:159], v[196:199], 0
	v_mfma_f32_16x16x32_f16 v[76:79], v[148:151], v[204:207], 0
	v_mfma_f32_16x16x32_f16 v[72:75], v[156:159], v[204:207], 0
	v_mfma_f32_16x16x32_f16 v[124:127], v[152:155], v[184:187], v[124:127]
	v_mfma_f32_16x16x32_f16 v[120:123], v[160:163], v[184:187], v[120:123]
	v_mfma_f32_16x16x32_f16 v[108:111], v[152:155], v[192:195], v[108:111]
	v_mfma_f32_16x16x32_f16 v[104:107], v[160:163], v[192:195], v[104:107]
	v_mfma_f32_16x16x32_f16 v[92:95], v[152:155], v[200:203], v[92:95]
	v_mfma_f32_16x16x32_f16 v[88:91], v[160:163], v[200:203], v[88:91]
	v_mfma_f32_16x16x32_f16 v[76:79], v[152:155], v[208:211], v[76:79]
	v_mfma_f32_16x16x32_f16 v[72:75], v[160:163], v[208:211], v[72:75]
	v_mfma_f32_16x16x32_f16 v[116:119], v[164:167], v[180:183], 0
	v_mfma_f32_16x16x32_f16 v[112:115], v[172:175], v[180:183], 0
	v_mfma_f32_16x16x32_f16 v[100:103], v[164:167], v[188:191], 0
	v_mfma_f32_16x16x32_f16 v[96:99], v[172:175], v[188:191], 0
	v_mfma_f32_16x16x32_f16 v[84:87], v[164:167], v[196:199], 0
	v_mfma_f32_16x16x32_f16 v[80:83], v[172:175], v[196:199], 0
	v_mfma_f32_16x16x32_f16 v[68:71], v[164:167], v[204:207], 0
	v_mfma_f32_16x16x32_f16 v[64:67], v[172:175], v[204:207], 0
	v_mfma_f32_16x16x32_f16 v[116:119], v[168:171], v[184:187], v[116:119]
	v_mfma_f32_16x16x32_f16 v[112:115], v[176:179], v[184:187], v[112:115]
	v_mfma_f32_16x16x32_f16 v[100:103], v[168:171], v[192:195], v[100:103]
	v_mfma_f32_16x16x32_f16 v[96:99], v[176:179], v[192:195], v[96:99]
	v_mfma_f32_16x16x32_f16 v[84:87], v[168:171], v[200:203], v[84:87]
	v_mfma_f32_16x16x32_f16 v[80:83], v[176:179], v[200:203], v[80:83]
	v_mfma_f32_16x16x32_f16 v[68:71], v[168:171], v[208:211], v[68:71]
	v_mfma_f32_16x16x32_f16 v[64:67], v[176:179], v[208:211], v[64:67]
	s_barrier
	s_add_i32 s48, s67, s66
	v_lshl_add_u64 v[212:213], s[16:17], 0, v[128:129]
	s_mov_b32 m0, s48
	ds_read_b128 v[180:183], v146 offset:16384
	ds_read_b128 v[184:187], v146 offset:17408
	ds_read_b128 v[188:191], v146 offset:18432
	ds_read_b128 v[192:195], v146 offset:19456
	ds_read_b128 v[196:199], v146 offset:20480
	ds_read_b128 v[200:203], v146 offset:21504
	ds_read_b128 v[204:207], v146 offset:22528
	ds_read_b128 v[208:211], v146 offset:23552
	global_load_lds_dwordx4 v[212:213], off
	s_add_i32 m0, s48, 0x2000
	s_add_u32 s48, s16, 0x40000
	v_lshl_add_u64 v[214:215], s[16:17], 0, v[134:135]
	s_addc_u32 s49, s17, 0
	s_add_i32 s47, s47, s66
	global_load_lds_dwordx4 v[214:215], off
	v_lshl_add_u64 v[216:217], s[48:49], 0, v[128:129]
	s_mov_b32 m0, s47
	v_lshl_add_u64 v[218:219], s[18:19], 0, v[132:133]
	global_load_lds_dwordx4 v[216:217], off
	v_lshl_add_u64 v[216:217], s[48:49], 0, v[134:135]
	s_add_i32 m0, s47, 0x2000
	s_nop 0
	global_load_lds_dwordx4 v[216:217], off
	v_lshl_add_u64 v[216:217], s[18:19], 0, v[130:131]
	s_mov_b32 m0, s30
	s_nop 0
	global_load_lds_dwordx4 v[216:217], off
	s_mov_b32 m0, s31
	s_nop 0
	global_load_lds_dwordx4 v[218:219], off
	s_waitcnt vmcnt(8)
	s_waitcnt lgkmcnt(0)
	s_barrier
	s_waitcnt lgkmcnt(0)
	v_mfma_f32_16x16x32_f16 v[60:63], v[148:151], v[180:183], 0
	v_mfma_f32_16x16x32_f16 v[56:59], v[156:159], v[180:183], 0
	v_mfma_f32_16x16x32_f16 v[44:47], v[148:151], v[188:191], 0
	v_mfma_f32_16x16x32_f16 v[40:43], v[156:159], v[188:191], 0
	v_mfma_f32_16x16x32_f16 v[28:31], v[148:151], v[196:199], 0
	v_mfma_f32_16x16x32_f16 v[24:27], v[156:159], v[196:199], 0
	v_mfma_f32_16x16x32_f16 v[12:15], v[148:151], v[204:207], 0
	v_mfma_f32_16x16x32_f16 v[8:11], v[156:159], v[204:207], 0
	v_mfma_f32_16x16x32_f16 v[60:63], v[152:155], v[184:187], v[60:63]
	v_mfma_f32_16x16x32_f16 v[56:59], v[160:163], v[184:187], v[56:59]
	v_mfma_f32_16x16x32_f16 v[44:47], v[152:155], v[192:195], v[44:47]
	v_mfma_f32_16x16x32_f16 v[40:43], v[160:163], v[192:195], v[40:43]
	v_mfma_f32_16x16x32_f16 v[28:31], v[152:155], v[200:203], v[28:31]
	v_mfma_f32_16x16x32_f16 v[24:27], v[160:163], v[200:203], v[24:27]
	v_mfma_f32_16x16x32_f16 v[12:15], v[152:155], v[208:211], v[12:15]
	v_mfma_f32_16x16x32_f16 v[8:11], v[160:163], v[208:211], v[8:11]
	v_mfma_f32_16x16x32_f16 v[52:55], v[164:167], v[180:183], 0
	v_mfma_f32_16x16x32_f16 v[48:51], v[172:175], v[180:183], 0
	v_mfma_f32_16x16x32_f16 v[36:39], v[164:167], v[188:191], 0
	v_mfma_f32_16x16x32_f16 v[32:35], v[172:175], v[188:191], 0
	v_mfma_f32_16x16x32_f16 v[20:23], v[164:167], v[196:199], 0
	v_mfma_f32_16x16x32_f16 v[16:19], v[172:175], v[196:199], 0
	v_mfma_f32_16x16x32_f16 v[4:7], v[164:167], v[204:207], 0
	v_mfma_f32_16x16x32_f16 v[0:3], v[172:175], v[204:207], 0
	v_mfma_f32_16x16x32_f16 v[52:55], v[168:171], v[184:187], v[52:55]
	v_mfma_f32_16x16x32_f16 v[48:51], v[176:179], v[184:187], v[48:51]
	v_mfma_f32_16x16x32_f16 v[36:39], v[168:171], v[192:195], v[36:39]
	v_mfma_f32_16x16x32_f16 v[32:35], v[176:179], v[192:195], v[32:35]
	v_mfma_f32_16x16x32_f16 v[20:23], v[168:171], v[200:203], v[20:23]
	v_mfma_f32_16x16x32_f16 v[16:19], v[176:179], v[200:203], v[16:19]
	v_mfma_f32_16x16x32_f16 v[4:7], v[168:171], v[208:211], v[4:7]
	v_mfma_f32_16x16x32_f16 v[0:3], v[176:179], v[208:211], v[0:3]
	s_barrier
	s_add_i32 s47, 0, 0x18000
	v_add_u32_e32 v147, s47, v145
	s_add_i32 s48, 0, 0x1c000
	ds_read_b128 v[148:151], v147
	ds_read_b128 v[152:155], v147 offset:1024
	ds_read_b128 v[156:159], v147 offset:2048
	ds_read_b128 v[160:163], v147 offset:3072
	v_add_u32_e32 v147, s48, v145
	ds_read_b128 v[164:167], v147
	ds_read_b128 v[168:171], v147 offset:1024
	ds_read_b128 v[172:175], v147 offset:2048
	ds_read_b128 v[176:179], v147 offset:3072
	s_add_u32 s18, s18, 0x40000
	s_addc_u32 s19, s19, 0
	s_mov_b32 m0, s34
	v_lshl_add_u64 v[220:221], s[18:19], 0, v[130:131]
	ds_read_b128 v[180:183], v146 offset:32768
	ds_read_b128 v[184:187], v146 offset:33792
	ds_read_b128 v[188:191], v146 offset:34816
	ds_read_b128 v[192:195], v146 offset:35840
	ds_read_b128 v[196:199], v146 offset:36864
	ds_read_b128 v[200:203], v146 offset:37888
	ds_read_b128 v[204:207], v146 offset:38912
	ds_read_b128 v[208:211], v146 offset:39936
	global_load_lds_dwordx4 v[220:221], off
	v_lshl_add_u64 v[220:221], s[18:19], 0, v[132:133]
	s_mov_b32 m0, s35
	s_nop 0
	global_load_lds_dwordx4 v[220:221], off
	s_waitcnt vmcnt(8)
	s_waitcnt lgkmcnt(0)
	s_barrier
	s_waitcnt lgkmcnt(0)
	v_mfma_f32_16x16x32_f16 v[124:127], v[148:151], v[180:183], v[124:127]
	v_mfma_f32_16x16x32_f16 v[120:123], v[156:159], v[180:183], v[120:123]
	v_mfma_f32_16x16x32_f16 v[108:111], v[148:151], v[188:191], v[108:111]
	v_mfma_f32_16x16x32_f16 v[104:107], v[156:159], v[188:191], v[104:107]
	v_mfma_f32_16x16x32_f16 v[92:95], v[148:151], v[196:199], v[92:95]
	v_mfma_f32_16x16x32_f16 v[88:91], v[156:159], v[196:199], v[88:91]
	v_mfma_f32_16x16x32_f16 v[76:79], v[148:151], v[204:207], v[76:79]
	v_mfma_f32_16x16x32_f16 v[72:75], v[156:159], v[204:207], v[72:75]
	v_mfma_f32_16x16x32_f16 v[124:127], v[152:155], v[184:187], v[124:127]
	v_mfma_f32_16x16x32_f16 v[120:123], v[160:163], v[184:187], v[120:123]
	v_mfma_f32_16x16x32_f16 v[108:111], v[152:155], v[192:195], v[108:111]
	v_mfma_f32_16x16x32_f16 v[104:107], v[160:163], v[192:195], v[104:107]
	v_mfma_f32_16x16x32_f16 v[92:95], v[152:155], v[200:203], v[92:95]
	v_mfma_f32_16x16x32_f16 v[88:91], v[160:163], v[200:203], v[88:91]
	v_mfma_f32_16x16x32_f16 v[76:79], v[152:155], v[208:211], v[76:79]
	v_mfma_f32_16x16x32_f16 v[72:75], v[160:163], v[208:211], v[72:75]
	v_mfma_f32_16x16x32_f16 v[116:119], v[164:167], v[180:183], v[116:119]
	v_mfma_f32_16x16x32_f16 v[112:115], v[172:175], v[180:183], v[112:115]
	v_mfma_f32_16x16x32_f16 v[100:103], v[164:167], v[188:191], v[100:103]
	v_mfma_f32_16x16x32_f16 v[96:99], v[172:175], v[188:191], v[96:99]
	v_mfma_f32_16x16x32_f16 v[84:87], v[164:167], v[196:199], v[84:87]
	v_mfma_f32_16x16x32_f16 v[80:83], v[172:175], v[196:199], v[80:83]
	v_mfma_f32_16x16x32_f16 v[68:71], v[164:167], v[204:207], v[68:71]
	v_mfma_f32_16x16x32_f16 v[64:67], v[172:175], v[204:207], v[64:67]
	v_mfma_f32_16x16x32_f16 v[116:119], v[168:171], v[184:187], v[116:119]
	v_mfma_f32_16x16x32_f16 v[112:115], v[176:179], v[184:187], v[112:115]
	v_mfma_f32_16x16x32_f16 v[100:103], v[168:171], v[192:195], v[100:103]
	v_mfma_f32_16x16x32_f16 v[96:99], v[176:179], v[192:195], v[96:99]
	v_mfma_f32_16x16x32_f16 v[84:87], v[168:171], v[200:203], v[84:87]
	v_mfma_f32_16x16x32_f16 v[80:83], v[176:179], v[200:203], v[80:83]
	v_mfma_f32_16x16x32_f16 v[68:71], v[168:171], v[208:211], v[68:71]
	v_mfma_f32_16x16x32_f16 v[64:67], v[176:179], v[208:211], v[64:67]
	s_barrier
	s_add_i32 s18, s47, s66
	v_lshl_add_u64 v[212:213], v[212:213], 0, s[6:7]
	s_mov_b32 m0, s18
	ds_read_b128 v[180:183], v146 offset:49152
	ds_read_b128 v[184:187], v146 offset:50176
	ds_read_b128 v[188:191], v146 offset:51200
	ds_read_b128 v[192:195], v146 offset:52224
	ds_read_b128 v[196:199], v146 offset:53248
	ds_read_b128 v[200:203], v146 offset:54272
	ds_read_b128 v[204:207], v146 offset:55296
	ds_read_b128 v[208:211], v146 offset:56320
	global_load_lds_dwordx4 v[212:213], off
	s_add_i32 m0, s18, 0x2000
	s_add_u32 s16, s16, 0x40080
	v_lshl_add_u64 v[212:213], v[214:215], 0, s[6:7]
	s_addc_u32 s17, s17, 0
	s_add_i32 s18, s48, s66
	global_load_lds_dwordx4 v[212:213], off
	v_lshl_add_u64 v[212:213], s[16:17], 0, v[128:129]
	s_mov_b32 m0, s18
	s_nop 0
	global_load_lds_dwordx4 v[212:213], off
	v_lshl_add_u64 v[212:213], s[16:17], 0, v[134:135]
	s_add_i32 m0, s18, 0x2000
	s_nop 0
	global_load_lds_dwordx4 v[212:213], off
	v_lshl_add_u64 v[212:213], v[216:217], 0, s[6:7]
	s_mov_b32 m0, s38
	s_nop 0
	global_load_lds_dwordx4 v[212:213], off
	v_lshl_add_u64 v[212:213], v[218:219], 0, s[6:7]
	s_mov_b32 m0, s39
	s_nop 0
	global_load_lds_dwordx4 v[212:213], off
	s_waitcnt vmcnt(8)
	s_waitcnt lgkmcnt(0)
	s_barrier
	s_waitcnt lgkmcnt(0)
	v_mfma_f32_16x16x32_f16 v[60:63], v[148:151], v[180:183], v[60:63]
	v_mfma_f32_16x16x32_f16 v[56:59], v[156:159], v[180:183], v[56:59]
	v_mfma_f32_16x16x32_f16 v[44:47], v[148:151], v[188:191], v[44:47]
	v_mfma_f32_16x16x32_f16 v[40:43], v[156:159], v[188:191], v[40:43]
	v_mfma_f32_16x16x32_f16 v[28:31], v[148:151], v[196:199], v[28:31]
	v_mfma_f32_16x16x32_f16 v[24:27], v[156:159], v[196:199], v[24:27]
	v_mfma_f32_16x16x32_f16 v[12:15], v[148:151], v[204:207], v[12:15]
	v_mfma_f32_16x16x32_f16 v[8:11], v[156:159], v[204:207], v[8:11]
	v_mfma_f32_16x16x32_f16 v[60:63], v[152:155], v[184:187], v[60:63]
	v_mfma_f32_16x16x32_f16 v[56:59], v[160:163], v[184:187], v[56:59]
	v_mfma_f32_16x16x32_f16 v[44:47], v[152:155], v[192:195], v[44:47]
	v_mfma_f32_16x16x32_f16 v[40:43], v[160:163], v[192:195], v[40:43]
	v_mfma_f32_16x16x32_f16 v[28:31], v[152:155], v[200:203], v[28:31]
	v_mfma_f32_16x16x32_f16 v[24:27], v[160:163], v[200:203], v[24:27]
	v_mfma_f32_16x16x32_f16 v[12:15], v[152:155], v[208:211], v[12:15]
	v_mfma_f32_16x16x32_f16 v[8:11], v[160:163], v[208:211], v[8:11]
	v_mfma_f32_16x16x32_f16 v[52:55], v[164:167], v[180:183], v[52:55]
	v_mfma_f32_16x16x32_f16 v[48:51], v[172:175], v[180:183], v[48:51]
	v_mfma_f32_16x16x32_f16 v[36:39], v[164:167], v[188:191], v[36:39]
	v_mfma_f32_16x16x32_f16 v[32:35], v[172:175], v[188:191], v[32:35]
	v_mfma_f32_16x16x32_f16 v[20:23], v[164:167], v[196:199], v[20:23]
	v_mfma_f32_16x16x32_f16 v[16:19], v[172:175], v[196:199], v[16:19]
	v_mfma_f32_16x16x32_f16 v[4:7], v[164:167], v[204:207], v[4:7]
	v_mfma_f32_16x16x32_f16 v[0:3], v[172:175], v[204:207], v[0:3]
	v_mfma_f32_16x16x32_f16 v[52:55], v[168:171], v[184:187], v[52:55]
	v_mfma_f32_16x16x32_f16 v[48:51], v[176:179], v[184:187], v[48:51]
	v_mfma_f32_16x16x32_f16 v[36:39], v[168:171], v[192:195], v[36:39]
	v_mfma_f32_16x16x32_f16 v[32:35], v[176:179], v[192:195], v[32:35]
	v_mfma_f32_16x16x32_f16 v[20:23], v[168:171], v[200:203], v[20:23]
	v_mfma_f32_16x16x32_f16 v[16:19], v[176:179], v[200:203], v[16:19]
	v_mfma_f32_16x16x32_f16 v[4:7], v[168:171], v[208:211], v[4:7]
	v_mfma_f32_16x16x32_f16 v[0:3], v[176:179], v[208:211], v[0:3]
	s_barrier
	s_add_i32 s46, s46, 2
	s_add_u32 s14, s14, 0x100
	s_addc_u32 s15, s15, 0
	s_cmp_gt_u32 s46, 13

.LBB0_1043:
	s_and_b64 s[44:45], s[40:41], exec
	s_cselect_b32 s5, s19, s35
	s_cselect_b32 s29, s18, s34
	s_cselect_b32 s33, s21, s43
	s_cselect_b32 s82, s20, s42
	s_add_u32 s34, s34, 0x40080
	s_addc_u32 s35, s35, 0
	s_add_u32 s83, s42, 0x100
	s_addc_u32 s84, s43, 0
	s_mov_b32 s85, -2
	v_add_u32_e32 v136, s67, v144
	ds_read_b128 v[156:159], v136
	ds_read_b128 v[160:163], v136 offset:1024
	ds_read_b128 v[164:167], v136 offset:2048
	ds_read_b128 v[168:171], v136 offset:3072
	ds_read_b128 v[172:175], v153
	ds_read_b128 v[176:179], v153 offset:1024
	ds_read_b128 v[180:183], v153 offset:2048
	ds_read_b128 v[184:187], v153 offset:3072
	s_add_u32 s42, s34, 0xfffc0080
	s_addc_u32 s43, s35, -1
	s_cmp_eq_u32 s85, 12
	s_cselect_b32 s45, s5, s43
	s_cselect_b32 s44, s29, s42
	s_cselect_b32 s43, s33, s84
	s_cselect_b32 s42, s82, s83
	v_lshl_add_u64 v[142:143], s[34:35], 0, v[138:139]
	s_add_i32 m0, s3, 0xc000
	ds_read_b128 v[188:191], v154
	ds_read_b128 v[192:195], v154 offset:1024
	ds_read_b128 v[196:199], v154 offset:2048
	ds_read_b128 v[200:203], v154 offset:3072
	ds_read_b128 v[204:207], v154 offset:4096
	ds_read_b128 v[208:211], v154 offset:5120
	ds_read_b128 v[212:215], v154 offset:6144
	ds_read_b128 v[216:219], v154 offset:7168
	global_load_lds_dwordx4 v[142:143], off
	v_lshl_add_u64 v[142:143], s[34:35], 0, v[140:141]
	s_add_i32 m0, s3, 0xe000
	s_nop 0
	global_load_lds_dwordx4 v[142:143], off
	s_waitcnt vmcnt(8)
	s_waitcnt lgkmcnt(0)
	s_barrier
	s_waitcnt lgkmcnt(0)
	v_mfma_f32_16x16x32_f16 v[124:127], v[156:159], v[188:191], 0
	v_mfma_f32_16x16x32_f16 v[120:123], v[164:167], v[188:191], 0
	v_mfma_f32_16x16x32_f16 v[108:111], v[156:159], v[196:199], 0
	v_mfma_f32_16x16x32_f16 v[104:107], v[164:167], v[196:199], 0
	v_mfma_f32_16x16x32_f16 v[92:95], v[156:159], v[204:207], 0
	v_mfma_f32_16x16x32_f16 v[88:91], v[164:167], v[204:207], 0
	v_mfma_f32_16x16x32_f16 v[76:79], v[156:159], v[212:215], 0
	v_mfma_f32_16x16x32_f16 v[72:75], v[164:167], v[212:215], 0
	v_mfma_f32_16x16x32_f16 v[124:127], v[160:163], v[192:195], v[124:127]
	v_mfma_f32_16x16x32_f16 v[120:123], v[168:171], v[192:195], v[120:123]
	v_mfma_f32_16x16x32_f16 v[108:111], v[160:163], v[200:203], v[108:111]
	v_mfma_f32_16x16x32_f16 v[104:107], v[168:171], v[200:203], v[104:107]
	v_mfma_f32_16x16x32_f16 v[92:95], v[160:163], v[208:211], v[92:95]
	v_mfma_f32_16x16x32_f16 v[88:91], v[168:171], v[208:211], v[88:91]
	v_mfma_f32_16x16x32_f16 v[76:79], v[160:163], v[216:219], v[76:79]
	v_mfma_f32_16x16x32_f16 v[72:75], v[168:171], v[216:219], v[72:75]
	v_mfma_f32_16x16x32_f16 v[116:119], v[172:175], v[188:191], 0
	v_mfma_f32_16x16x32_f16 v[112:115], v[180:183], v[188:191], 0
	v_mfma_f32_16x16x32_f16 v[100:103], v[172:175], v[196:199], 0
	v_mfma_f32_16x16x32_f16 v[96:99], v[180:183], v[196:199], 0
	v_mfma_f32_16x16x32_f16 v[84:87], v[172:175], v[204:207], 0
	v_mfma_f32_16x16x32_f16 v[80:83], v[180:183], v[204:207], 0
	v_mfma_f32_16x16x32_f16 v[68:71], v[172:175], v[212:215], 0
	v_mfma_f32_16x16x32_f16 v[64:67], v[180:183], v[212:215], 0
	v_mfma_f32_16x16x32_f16 v[116:119], v[176:179], v[192:195], v[116:119]
	v_mfma_f32_16x16x32_f16 v[112:115], v[184:187], v[192:195], v[112:115]
	v_mfma_f32_16x16x32_f16 v[100:103], v[176:179], v[200:203], v[100:103]
	v_mfma_f32_16x16x32_f16 v[96:99], v[184:187], v[200:203], v[96:99]
	v_mfma_f32_16x16x32_f16 v[84:87], v[176:179], v[208:211], v[84:87]
	v_mfma_f32_16x16x32_f16 v[80:83], v[184:187], v[208:211], v[80:83]
	v_mfma_f32_16x16x32_f16 v[68:71], v[176:179], v[216:219], v[68:71]
	v_mfma_f32_16x16x32_f16 v[64:67], v[184:187], v[216:219], v[64:67]
	s_barrier
	s_add_i32 s86, s67, s66
	v_lshl_add_u64 v[142:143], s[42:43], 0, v[130:131]
	s_mov_b32 m0, s86
	ds_read_b128 v[188:191], v154 offset:16384
	ds_read_b128 v[192:195], v154 offset:17408
	ds_read_b128 v[196:199], v154 offset:18432
	ds_read_b128 v[200:203], v154 offset:19456
	ds_read_b128 v[204:207], v154 offset:20480
	ds_read_b128 v[208:211], v154 offset:21504
	ds_read_b128 v[212:215], v154 offset:22528
	ds_read_b128 v[216:219], v154 offset:23552
	global_load_lds_dwordx4 v[142:143], off
	s_add_i32 m0, s86, 0x2000
	s_add_u32 s86, s42, 0x40000
	v_lshl_add_u64 v[220:221], s[42:43], 0, v[134:135]
	s_addc_u32 s87, s43, 0
	s_add_i32 s88, s70, s66
	global_load_lds_dwordx4 v[220:221], off
	v_lshl_add_u64 v[222:223], s[86:87], 0, v[130:131]
	s_mov_b32 m0, s88
	v_lshl_add_u64 v[224:225], s[44:45], 0, v[132:133]
	global_load_lds_dwordx4 v[222:223], off
	v_lshl_add_u64 v[222:223], s[86:87], 0, v[134:135]
	s_add_i32 m0, s88, 0x2000
	s_nop 0
	global_load_lds_dwordx4 v[222:223], off
	v_lshl_add_u64 v[222:223], s[44:45], 0, v[128:129]
	s_mov_b32 m0, s3
	s_nop 0
	global_load_lds_dwordx4 v[222:223], off
	s_mov_b32 m0, s31
	s_nop 0
	global_load_lds_dwordx4 v[224:225], off
	s_waitcnt vmcnt(8)
	s_waitcnt lgkmcnt(0)
	s_barrier
	s_waitcnt lgkmcnt(0)
	v_mfma_f32_16x16x32_f16 v[60:63], v[156:159], v[188:191], 0
	v_mfma_f32_16x16x32_f16 v[56:59], v[164:167], v[188:191], 0
	v_mfma_f32_16x16x32_f16 v[44:47], v[156:159], v[196:199], 0
	v_mfma_f32_16x16x32_f16 v[40:43], v[164:167], v[196:199], 0
	v_mfma_f32_16x16x32_f16 v[28:31], v[156:159], v[204:207], 0
	v_mfma_f32_16x16x32_f16 v[24:27], v[164:167], v[204:207], 0
	v_mfma_f32_16x16x32_f16 v[12:15], v[156:159], v[212:215], 0
	v_mfma_f32_16x16x32_f16 v[8:11], v[164:167], v[212:215], 0
	v_mfma_f32_16x16x32_f16 v[60:63], v[160:163], v[192:195], v[60:63]
	v_mfma_f32_16x16x32_f16 v[56:59], v[168:171], v[192:195], v[56:59]
	v_mfma_f32_16x16x32_f16 v[44:47], v[160:163], v[200:203], v[44:47]
	v_mfma_f32_16x16x32_f16 v[40:43], v[168:171], v[200:203], v[40:43]
	v_mfma_f32_16x16x32_f16 v[28:31], v[160:163], v[208:211], v[28:31]
	v_mfma_f32_16x16x32_f16 v[24:27], v[168:171], v[208:211], v[24:27]
	v_mfma_f32_16x16x32_f16 v[12:15], v[160:163], v[216:219], v[12:15]
	v_mfma_f32_16x16x32_f16 v[8:11], v[168:171], v[216:219], v[8:11]
	v_mfma_f32_16x16x32_f16 v[52:55], v[172:175], v[188:191], 0
	v_mfma_f32_16x16x32_f16 v[48:51], v[180:183], v[188:191], 0
	v_mfma_f32_16x16x32_f16 v[36:39], v[172:175], v[196:199], 0
	v_mfma_f32_16x16x32_f16 v[32:35], v[180:183], v[196:199], 0
	v_mfma_f32_16x16x32_f16 v[20:23], v[172:175], v[204:207], 0
	v_mfma_f32_16x16x32_f16 v[16:19], v[180:183], v[204:207], 0
	v_mfma_f32_16x16x32_f16 v[4:7], v[172:175], v[212:215], 0
	v_mfma_f32_16x16x32_f16 v[0:3], v[180:183], v[212:215], 0
	v_mfma_f32_16x16x32_f16 v[52:55], v[176:179], v[192:195], v[52:55]
	v_mfma_f32_16x16x32_f16 v[48:51], v[184:187], v[192:195], v[48:51]
	v_mfma_f32_16x16x32_f16 v[36:39], v[176:179], v[200:203], v[36:39]
	v_mfma_f32_16x16x32_f16 v[32:35], v[184:187], v[200:203], v[32:35]
	v_mfma_f32_16x16x32_f16 v[20:23], v[176:179], v[208:211], v[20:23]
	v_mfma_f32_16x16x32_f16 v[16:19], v[184:187], v[208:211], v[16:19]
	v_mfma_f32_16x16x32_f16 v[4:7], v[176:179], v[216:219], v[4:7]
	v_mfma_f32_16x16x32_f16 v[0:3], v[184:187], v[216:219], v[0:3]
	s_barrier
	s_add_i32 s86, 0, 0x18000
	v_add_u32_e32 v136, s86, v144
	ds_read_b128 v[156:159], v136
	ds_read_b128 v[160:163], v136 offset:1024
	ds_read_b128 v[164:167], v136 offset:2048
	ds_read_b128 v[168:171], v136 offset:3072
	ds_read_b128 v[172:175], v155
	ds_read_b128 v[176:179], v155 offset:1024
	ds_read_b128 v[180:183], v155 offset:2048
	ds_read_b128 v[184:187], v155 offset:3072
	s_add_u32 s44, s44, 0x40000
	s_addc_u32 s45, s45, 0
	s_mov_b32 m0, s46
	v_lshl_add_u64 v[226:227], s[44:45], 0, v[128:129]
	ds_read_b128 v[188:191], v154 offset:32768
	ds_read_b128 v[192:195], v154 offset:33792
	ds_read_b128 v[196:199], v154 offset:34816
	ds_read_b128 v[200:203], v154 offset:35840
	ds_read_b128 v[204:207], v154 offset:36864
	ds_read_b128 v[208:211], v154 offset:37888
	ds_read_b128 v[212:215], v154 offset:38912
	ds_read_b128 v[216:219], v154 offset:39936
	global_load_lds_dwordx4 v[226:227], off
	v_lshl_add_u64 v[226:227], s[44:45], 0, v[132:133]
	s_mov_b32 m0, s47
	s_nop 0
	global_load_lds_dwordx4 v[226:227], off
	s_waitcnt vmcnt(8)
	s_waitcnt lgkmcnt(0)
	s_barrier
	s_waitcnt lgkmcnt(0)
	v_mfma_f32_16x16x32_f16 v[124:127], v[156:159], v[188:191], v[124:127]
	v_mfma_f32_16x16x32_f16 v[120:123], v[164:167], v[188:191], v[120:123]
	v_mfma_f32_16x16x32_f16 v[108:111], v[156:159], v[196:199], v[108:111]
	v_mfma_f32_16x16x32_f16 v[104:107], v[164:167], v[196:199], v[104:107]
	v_mfma_f32_16x16x32_f16 v[92:95], v[156:159], v[204:207], v[92:95]
	v_mfma_f32_16x16x32_f16 v[88:91], v[164:167], v[204:207], v[88:91]
	v_mfma_f32_16x16x32_f16 v[76:79], v[156:159], v[212:215], v[76:79]
	v_mfma_f32_16x16x32_f16 v[72:75], v[164:167], v[212:215], v[72:75]
	v_mfma_f32_16x16x32_f16 v[124:127], v[160:163], v[192:195], v[124:127]
	v_mfma_f32_16x16x32_f16 v[120:123], v[168:171], v[192:195], v[120:123]
	v_mfma_f32_16x16x32_f16 v[108:111], v[160:163], v[200:203], v[108:111]
	v_mfma_f32_16x16x32_f16 v[104:107], v[168:171], v[200:203], v[104:107]
	v_mfma_f32_16x16x32_f16 v[92:95], v[160:163], v[208:211], v[92:95]
	v_mfma_f32_16x16x32_f16 v[88:91], v[168:171], v[208:211], v[88:91]
	v_mfma_f32_16x16x32_f16 v[76:79], v[160:163], v[216:219], v[76:79]
	v_mfma_f32_16x16x32_f16 v[72:75], v[168:171], v[216:219], v[72:75]
	v_mfma_f32_16x16x32_f16 v[116:119], v[172:175], v[188:191], v[116:119]
	v_mfma_f32_16x16x32_f16 v[112:115], v[180:183], v[188:191], v[112:115]
	v_mfma_f32_16x16x32_f16 v[100:103], v[172:175], v[196:199], v[100:103]
	v_mfma_f32_16x16x32_f16 v[96:99], v[180:183], v[196:199], v[96:99]
	v_mfma_f32_16x16x32_f16 v[84:87], v[172:175], v[204:207], v[84:87]
	v_mfma_f32_16x16x32_f16 v[80:83], v[180:183], v[204:207], v[80:83]
	v_mfma_f32_16x16x32_f16 v[68:71], v[172:175], v[212:215], v[68:71]
	v_mfma_f32_16x16x32_f16 v[64:67], v[180:183], v[212:215], v[64:67]
	v_mfma_f32_16x16x32_f16 v[116:119], v[176:179], v[192:195], v[116:119]
	v_mfma_f32_16x16x32_f16 v[112:115], v[184:187], v[192:195], v[112:115]
	v_mfma_f32_16x16x32_f16 v[100:103], v[176:179], v[200:203], v[100:103]
	v_mfma_f32_16x16x32_f16 v[96:99], v[184:187], v[200:203], v[96:99]
	v_mfma_f32_16x16x32_f16 v[84:87], v[176:179], v[208:211], v[84:87]
	v_mfma_f32_16x16x32_f16 v[80:83], v[184:187], v[208:211], v[80:83]
	v_mfma_f32_16x16x32_f16 v[68:71], v[176:179], v[216:219], v[68:71]
	v_mfma_f32_16x16x32_f16 v[64:67], v[184:187], v[216:219], v[64:67]
	s_barrier
	s_add_i32 s44, s86, s66
	v_lshl_add_u64 v[142:143], v[142:143], 0, s[6:7]
	s_mov_b32 m0, s44
	ds_read_b128 v[188:191], v154 offset:49152
	ds_read_b128 v[192:195], v154 offset:50176
	ds_read_b128 v[196:199], v154 offset:51200
	ds_read_b128 v[200:203], v154 offset:52224
	ds_read_b128 v[204:207], v154 offset:53248
	ds_read_b128 v[208:211], v154 offset:54272
	ds_read_b128 v[212:215], v154 offset:55296
	ds_read_b128 v[216:219], v154 offset:56320
	global_load_lds_dwordx4 v[142:143], off
	s_add_i32 m0, s44, 0x2000
	s_add_u32 s42, s42, 0x40080
	v_lshl_add_u64 v[142:143], v[220:221], 0, s[6:7]
	s_addc_u32 s43, s43, 0
	s_add_i32 s44, s71, s66
	global_load_lds_dwordx4 v[142:143], off
	v_lshl_add_u64 v[142:143], s[42:43], 0, v[130:131]
	s_mov_b32 m0, s44
	s_nop 0
	global_load_lds_dwordx4 v[142:143], off
	v_lshl_add_u64 v[142:143], s[42:43], 0, v[134:135]
	s_add_i32 m0, s44, 0x2000
	s_nop 0
	global_load_lds_dwordx4 v[142:143], off
	v_lshl_add_u64 v[142:143], v[222:223], 0, s[6:7]
	s_mov_b32 m0, s48
	s_nop 0
	global_load_lds_dwordx4 v[142:143], off
	v_lshl_add_u64 v[142:143], v[224:225], 0, s[6:7]
	s_mov_b32 m0, s49
	s_nop 0
	global_load_lds_dwordx4 v[142:143], off
	s_waitcnt vmcnt(8)
	s_waitcnt lgkmcnt(0)
	s_barrier
	s_waitcnt lgkmcnt(0)
	v_mfma_f32_16x16x32_f16 v[60:63], v[156:159], v[188:191], v[60:63]
	v_mfma_f32_16x16x32_f16 v[56:59], v[164:167], v[188:191], v[56:59]
	v_mfma_f32_16x16x32_f16 v[44:47], v[156:159], v[196:199], v[44:47]
	v_mfma_f32_16x16x32_f16 v[40:43], v[164:167], v[196:199], v[40:43]
	v_mfma_f32_16x16x32_f16 v[28:31], v[156:159], v[204:207], v[28:31]
	v_mfma_f32_16x16x32_f16 v[24:27], v[164:167], v[204:207], v[24:27]
	v_mfma_f32_16x16x32_f16 v[12:15], v[156:159], v[212:215], v[12:15]
	v_mfma_f32_16x16x32_f16 v[8:11], v[164:167], v[212:215], v[8:11]
	v_mfma_f32_16x16x32_f16 v[60:63], v[160:163], v[192:195], v[60:63]
	v_mfma_f32_16x16x32_f16 v[56:59], v[168:171], v[192:195], v[56:59]
	v_mfma_f32_16x16x32_f16 v[44:47], v[160:163], v[200:203], v[44:47]
	v_mfma_f32_16x16x32_f16 v[40:43], v[168:171], v[200:203], v[40:43]
	v_mfma_f32_16x16x32_f16 v[28:31], v[160:163], v[208:211], v[28:31]
	v_mfma_f32_16x16x32_f16 v[24:27], v[168:171], v[208:211], v[24:27]
	v_mfma_f32_16x16x32_f16 v[12:15], v[160:163], v[216:219], v[12:15]
	v_mfma_f32_16x16x32_f16 v[8:11], v[168:171], v[216:219], v[8:11]
	v_mfma_f32_16x16x32_f16 v[52:55], v[172:175], v[188:191], v[52:55]
	v_mfma_f32_16x16x32_f16 v[48:51], v[180:183], v[188:191], v[48:51]
	v_mfma_f32_16x16x32_f16 v[36:39], v[172:175], v[196:199], v[36:39]
	v_mfma_f32_16x16x32_f16 v[32:35], v[180:183], v[196:199], v[32:35]
	v_mfma_f32_16x16x32_f16 v[20:23], v[172:175], v[204:207], v[20:23]
	v_mfma_f32_16x16x32_f16 v[16:19], v[180:183], v[204:207], v[16:19]
	v_mfma_f32_16x16x32_f16 v[4:7], v[172:175], v[212:215], v[4:7]
	v_mfma_f32_16x16x32_f16 v[0:3], v[180:183], v[212:215], v[0:3]
	v_mfma_f32_16x16x32_f16 v[52:55], v[176:179], v[192:195], v[52:55]
	v_mfma_f32_16x16x32_f16 v[48:51], v[184:187], v[192:195], v[48:51]
	v_mfma_f32_16x16x32_f16 v[36:39], v[176:179], v[200:203], v[36:39]
	v_mfma_f32_16x16x32_f16 v[32:35], v[184:187], v[200:203], v[32:35]
	v_mfma_f32_16x16x32_f16 v[20:23], v[176:179], v[208:211], v[20:23]
	v_mfma_f32_16x16x32_f16 v[16:19], v[184:187], v[208:211], v[16:19]
	v_mfma_f32_16x16x32_f16 v[4:7], v[176:179], v[216:219], v[4:7]
	v_mfma_f32_16x16x32_f16 v[0:3], v[184:187], v[216:219], v[0:3]
	s_barrier
	s_add_i32 s85, s85, 2
	s_add_u32 s34, s34, 0x100
	s_addc_u32 s35, s35, 0
	s_add_u32 s83, s83, 0x100
	s_addc_u32 s84, s84, 0
	s_cmp_gt_u32 s85, 13

.LBB0_1231:
	v_and_b32_e32 v142, 15, v2
	v_and_b32_e32 v143, 48, v2
	v_lshlrev_b32_e32 v2, 2, v2
	s_lshl_b32 s14, s14, 21
	v_lshl_or_b32 v7, v142, 6, v143
	v_and_b32_e32 v2, 32, v2
	s_and_b32 s14, s14, 0x3800000
	s_lshl_b32 s15, s15, 19
	v_bitop3_b32 v8, v7, s52, v2 bitop3:0xde
	v_bitop3_b32 v144, v7, s53, v2 bitop3:0xde
	s_add_i32 s14, s14, s15
	v_lshlrev_b32_e32 v2, 14, v0
	s_add_u32 s38, s76, s14
	v_and_b32_e32 v2, 0xffff8000, v2
	s_addc_u32 s39, s77, 0
	v_lshl_add_u32 v1, v1, 11, v2
	v_and_b32_e32 v0, 1, v0
	v_lshl_or_b32 v0, v0, 6, v1
	s_add_u32 s14, s3, s14
	v_lshl_add_u32 v0, v3, 1, v0
	v_mov_b32_e32 v1, v129
	s_addc_u32 s15, s28, 0
	v_lshl_add_u64 v[136:137], s[14:15], 0, v[0:1]
	v_lshlrev_b32_e32 v0, 14, v4
	v_and_b32_e32 v0, 0xffff8000, v0
	v_lshl_add_u32 v0, v5, 11, v0
	v_and_b32_e32 v1, 1, v4
	v_lshl_or_b32 v0, v1, 6, v0
	s_waitcnt vmcnt(8)
	s_barrier
	s_waitcnt vmcnt(6)
	v_lshl_add_u32 v0, v6, 1, v0
	v_mov_b32_e32 v1, v129
	v_lshl_add_u64 v[138:139], s[14:15], 0, v[0:1]
	s_add_u32 s40, s29, s16
	s_addc_u32 s41, s33, 0
	s_mov_b32 s42, -2
	s_mov_b64 s[14:15], 0
	v_add_u32_e32 v145, 0, v8
	s_barrier
	s_add_u32 s16, s38, s14
	s_addc_u32 s17, s39, s15
	s_add_u32 s16, s16, 0x13d00100
	s_addc_u32 s17, s17, 0
	s_add_u32 s43, s40, s14
	s_addc_u32 s44, s41, s15
	s_cmpk_eq_i32 s14, 0x700
	s_cselect_b32 s19, s11, s17
	s_cselect_b32 s18, s10, s16
	s_cselect_b32 s17, s13, s44
	s_cselect_b32 s16, s12, s43
	s_add_i32 s43, 0, 0x14000
	v_add_u32_e32 v158, s67, v144
	v_add_u32_e32 v174, s43, v144
	ds_read_b128 v[146:149], v158
	ds_read_b128 v[150:153], v158 offset:1024
	ds_read_b128 v[154:157], v158 offset:2048
	ds_read_b128 v[158:161], v158 offset:3072
	ds_read_b128 v[162:165], v174
	ds_read_b128 v[166:169], v174 offset:1024
	ds_read_b128 v[170:173], v174 offset:2048
	ds_read_b128 v[174:177], v174 offset:3072
	v_lshl_add_u64 v[210:211], v[136:137], 0, s[14:15]
	s_add_i32 m0, s30, 0xc000
	ds_read_b128 v[178:181], v145
	ds_read_b128 v[182:185], v145 offset:1024
	ds_read_b128 v[186:189], v145 offset:2048
	ds_read_b128 v[190:193], v145 offset:3072
	ds_read_b128 v[194:197], v145 offset:4096
	ds_read_b128 v[198:201], v145 offset:5120
	ds_read_b128 v[202:205], v145 offset:6144
	ds_read_b128 v[206:209], v145 offset:7168
	global_load_lds_dwordx4 v[210:211], off
	v_lshl_add_u64 v[210:211], v[138:139], 0, s[14:15]
	s_add_i32 m0, s30, 0xe000
	s_nop 0
	global_load_lds_dwordx4 v[210:211], off
	s_waitcnt vmcnt(8)
	s_waitcnt lgkmcnt(0)
	s_barrier
	s_waitcnt lgkmcnt(0)
	v_mfma_f32_16x16x32_f16 v[124:127], v[146:149], v[178:181], 0
	v_mfma_f32_16x16x32_f16 v[120:123], v[154:157], v[178:181], 0
	v_mfma_f32_16x16x32_f16 v[108:111], v[146:149], v[186:189], 0
	v_mfma_f32_16x16x32_f16 v[104:107], v[154:157], v[186:189], 0
	v_mfma_f32_16x16x32_f16 v[92:95], v[146:149], v[194:197], 0
	v_mfma_f32_16x16x32_f16 v[88:91], v[154:157], v[194:197], 0
	v_mfma_f32_16x16x32_f16 v[76:79], v[146:149], v[202:205], 0
	v_mfma_f32_16x16x32_f16 v[72:75], v[154:157], v[202:205], 0
	v_mfma_f32_16x16x32_f16 v[124:127], v[150:153], v[182:185], v[124:127]
	v_mfma_f32_16x16x32_f16 v[120:123], v[158:161], v[182:185], v[120:123]
	v_mfma_f32_16x16x32_f16 v[108:111], v[150:153], v[190:193], v[108:111]
	v_mfma_f32_16x16x32_f16 v[104:107], v[158:161], v[190:193], v[104:107]
	v_mfma_f32_16x16x32_f16 v[92:95], v[150:153], v[198:201], v[92:95]
	v_mfma_f32_16x16x32_f16 v[88:91], v[158:161], v[198:201], v[88:91]
	v_mfma_f32_16x16x32_f16 v[76:79], v[150:153], v[206:209], v[76:79]
	v_mfma_f32_16x16x32_f16 v[72:75], v[158:161], v[206:209], v[72:75]
	v_mfma_f32_16x16x32_f16 v[116:119], v[162:165], v[178:181], 0
	v_mfma_f32_16x16x32_f16 v[112:115], v[170:173], v[178:181], 0
	v_mfma_f32_16x16x32_f16 v[100:103], v[162:165], v[186:189], 0
	v_mfma_f32_16x16x32_f16 v[96:99], v[170:173], v[186:189], 0
	v_mfma_f32_16x16x32_f16 v[84:87], v[162:165], v[194:197], 0
	v_mfma_f32_16x16x32_f16 v[80:83], v[170:173], v[194:197], 0
	v_mfma_f32_16x16x32_f16 v[68:71], v[162:165], v[202:205], 0
	v_mfma_f32_16x16x32_f16 v[64:67], v[170:173], v[202:205], 0
	v_mfma_f32_16x16x32_f16 v[116:119], v[166:169], v[182:185], v[116:119]
	v_mfma_f32_16x16x32_f16 v[112:115], v[174:177], v[182:185], v[112:115]
	v_mfma_f32_16x16x32_f16 v[100:103], v[166:169], v[190:193], v[100:103]
	v_mfma_f32_16x16x32_f16 v[96:99], v[174:177], v[190:193], v[96:99]
	v_mfma_f32_16x16x32_f16 v[84:87], v[166:169], v[198:201], v[84:87]
	v_mfma_f32_16x16x32_f16 v[80:83], v[174:177], v[198:201], v[80:83]
	v_mfma_f32_16x16x32_f16 v[68:71], v[166:169], v[206:209], v[68:71]
	v_mfma_f32_16x16x32_f16 v[64:67], v[174:177], v[206:209], v[64:67]
	s_barrier
	s_add_i32 s44, s67, s66
	v_lshl_add_u64 v[210:211], s[16:17], 0, v[128:129]
	s_mov_b32 m0, s44
	ds_read_b128 v[178:181], v145 offset:16384
	ds_read_b128 v[182:185], v145 offset:17408
	ds_read_b128 v[186:189], v145 offset:18432
	ds_read_b128 v[190:193], v145 offset:19456
	ds_read_b128 v[194:197], v145 offset:20480
	ds_read_b128 v[198:201], v145 offset:21504
	ds_read_b128 v[202:205], v145 offset:22528
	ds_read_b128 v[206:209], v145 offset:23552
	global_load_lds_dwordx4 v[210:211], off
	s_add_i32 m0, s44, 0x2000
	s_add_u32 s44, s16, 0x40000
	v_lshl_add_u64 v[212:213], s[16:17], 0, v[134:135]
	s_addc_u32 s45, s17, 0
	s_add_i32 s43, s43, s66
	global_load_lds_dwordx4 v[212:213], off
	v_lshl_add_u64 v[214:215], s[44:45], 0, v[128:129]
	s_mov_b32 m0, s43
	v_lshl_add_u64 v[216:217], s[18:19], 0, v[132:133]
	global_load_lds_dwordx4 v[214:215], off
	v_lshl_add_u64 v[214:215], s[44:45], 0, v[134:135]
	s_add_i32 m0, s43, 0x2000
	s_nop 0
	global_load_lds_dwordx4 v[214:215], off
	v_lshl_add_u64 v[214:215], s[18:19], 0, v[130:131]
	s_mov_b32 m0, s30
	s_nop 0
	global_load_lds_dwordx4 v[214:215], off
	s_mov_b32 m0, s31
	s_nop 0
	global_load_lds_dwordx4 v[216:217], off
	s_waitcnt vmcnt(8)
	s_waitcnt lgkmcnt(0)
	s_barrier
	s_waitcnt lgkmcnt(0)
	v_mfma_f32_16x16x32_f16 v[60:63], v[146:149], v[178:181], 0
	v_mfma_f32_16x16x32_f16 v[56:59], v[154:157], v[178:181], 0
	v_mfma_f32_16x16x32_f16 v[44:47], v[146:149], v[186:189], 0
	v_mfma_f32_16x16x32_f16 v[40:43], v[154:157], v[186:189], 0
	v_mfma_f32_16x16x32_f16 v[28:31], v[146:149], v[194:197], 0
	v_mfma_f32_16x16x32_f16 v[24:27], v[154:157], v[194:197], 0
	v_mfma_f32_16x16x32_f16 v[12:15], v[146:149], v[202:205], 0
	v_mfma_f32_16x16x32_f16 v[8:11], v[154:157], v[202:205], 0
	v_mfma_f32_16x16x32_f16 v[60:63], v[150:153], v[182:185], v[60:63]
	v_mfma_f32_16x16x32_f16 v[56:59], v[158:161], v[182:185], v[56:59]
	v_mfma_f32_16x16x32_f16 v[44:47], v[150:153], v[190:193], v[44:47]
	v_mfma_f32_16x16x32_f16 v[40:43], v[158:161], v[190:193], v[40:43]
	v_mfma_f32_16x16x32_f16 v[28:31], v[150:153], v[198:201], v[28:31]
	v_mfma_f32_16x16x32_f16 v[24:27], v[158:161], v[198:201], v[24:27]
	v_mfma_f32_16x16x32_f16 v[12:15], v[150:153], v[206:209], v[12:15]
	v_mfma_f32_16x16x32_f16 v[8:11], v[158:161], v[206:209], v[8:11]
	v_mfma_f32_16x16x32_f16 v[52:55], v[162:165], v[178:181], 0
	v_mfma_f32_16x16x32_f16 v[48:51], v[170:173], v[178:181], 0
	v_mfma_f32_16x16x32_f16 v[36:39], v[162:165], v[186:189], 0
	v_mfma_f32_16x16x32_f16 v[32:35], v[170:173], v[186:189], 0
	v_mfma_f32_16x16x32_f16 v[20:23], v[162:165], v[194:197], 0
	v_mfma_f32_16x16x32_f16 v[16:19], v[170:173], v[194:197], 0
	v_mfma_f32_16x16x32_f16 v[4:7], v[162:165], v[202:205], 0
	v_mfma_f32_16x16x32_f16 v[0:3], v[170:173], v[202:205], 0
	v_mfma_f32_16x16x32_f16 v[52:55], v[166:169], v[182:185], v[52:55]
	v_mfma_f32_16x16x32_f16 v[48:51], v[174:177], v[182:185], v[48:51]
	v_mfma_f32_16x16x32_f16 v[36:39], v[166:169], v[190:193], v[36:39]
	v_mfma_f32_16x16x32_f16 v[32:35], v[174:177], v[190:193], v[32:35]
	v_mfma_f32_16x16x32_f16 v[20:23], v[166:169], v[198:201], v[20:23]
	v_mfma_f32_16x16x32_f16 v[16:19], v[174:177], v[198:201], v[16:19]
	v_mfma_f32_16x16x32_f16 v[4:7], v[166:169], v[206:209], v[4:7]
	v_mfma_f32_16x16x32_f16 v[0:3], v[174:177], v[206:209], v[0:3]
	s_barrier
	s_add_i32 s43, 0, 0x18000
	s_add_i32 s44, 0, 0x1c000
	v_add_u32_e32 v158, s43, v144
	v_add_u32_e32 v174, s44, v144
	ds_read_b128 v[146:149], v158
	ds_read_b128 v[150:153], v158 offset:1024
	ds_read_b128 v[154:157], v158 offset:2048
	ds_read_b128 v[158:161], v158 offset:3072
	ds_read_b128 v[162:165], v174
	ds_read_b128 v[166:169], v174 offset:1024
	ds_read_b128 v[170:173], v174 offset:2048
	ds_read_b128 v[174:177], v174 offset:3072
	s_add_u32 s18, s18, 0x40000
	s_addc_u32 s19, s19, 0
	s_mov_b32 m0, s34
	v_lshl_add_u64 v[218:219], s[18:19], 0, v[130:131]
	ds_read_b128 v[178:181], v145 offset:32768
	ds_read_b128 v[182:185], v145 offset:33792
	ds_read_b128 v[186:189], v145 offset:34816
	ds_read_b128 v[190:193], v145 offset:35840
	ds_read_b128 v[194:197], v145 offset:36864
	ds_read_b128 v[198:201], v145 offset:37888
	ds_read_b128 v[202:205], v145 offset:38912
	ds_read_b128 v[206:209], v145 offset:39936
	global_load_lds_dwordx4 v[218:219], off
	v_lshl_add_u64 v[218:219], s[18:19], 0, v[132:133]
	s_mov_b32 m0, s35
	s_nop 0
	global_load_lds_dwordx4 v[218:219], off
	s_waitcnt vmcnt(8)
	s_waitcnt lgkmcnt(0)
	s_barrier
	s_waitcnt lgkmcnt(0)
	v_mfma_f32_16x16x32_f16 v[124:127], v[146:149], v[178:181], v[124:127]
	v_mfma_f32_16x16x32_f16 v[120:123], v[154:157], v[178:181], v[120:123]
	v_mfma_f32_16x16x32_f16 v[108:111], v[146:149], v[186:189], v[108:111]
	v_mfma_f32_16x16x32_f16 v[104:107], v[154:157], v[186:189], v[104:107]
	v_mfma_f32_16x16x32_f16 v[92:95], v[146:149], v[194:197], v[92:95]
	v_mfma_f32_16x16x32_f16 v[88:91], v[154:157], v[194:197], v[88:91]
	v_mfma_f32_16x16x32_f16 v[76:79], v[146:149], v[202:205], v[76:79]
	v_mfma_f32_16x16x32_f16 v[72:75], v[154:157], v[202:205], v[72:75]
	v_mfma_f32_16x16x32_f16 v[124:127], v[150:153], v[182:185], v[124:127]
	v_mfma_f32_16x16x32_f16 v[120:123], v[158:161], v[182:185], v[120:123]
	v_mfma_f32_16x16x32_f16 v[108:111], v[150:153], v[190:193], v[108:111]
	v_mfma_f32_16x16x32_f16 v[104:107], v[158:161], v[190:193], v[104:107]
	v_mfma_f32_16x16x32_f16 v[92:95], v[150:153], v[198:201], v[92:95]
	v_mfma_f32_16x16x32_f16 v[88:91], v[158:161], v[198:201], v[88:91]
	v_mfma_f32_16x16x32_f16 v[76:79], v[150:153], v[206:209], v[76:79]
	v_mfma_f32_16x16x32_f16 v[72:75], v[158:161], v[206:209], v[72:75]
	v_mfma_f32_16x16x32_f16 v[116:119], v[162:165], v[178:181], v[116:119]
	v_mfma_f32_16x16x32_f16 v[112:115], v[170:173], v[178:181], v[112:115]
	v_mfma_f32_16x16x32_f16 v[100:103], v[162:165], v[186:189], v[100:103]
	v_mfma_f32_16x16x32_f16 v[96:99], v[170:173], v[186:189], v[96:99]
	v_mfma_f32_16x16x32_f16 v[84:87], v[162:165], v[194:197], v[84:87]
	v_mfma_f32_16x16x32_f16 v[80:83], v[170:173], v[194:197], v[80:83]
	v_mfma_f32_16x16x32_f16 v[68:71], v[162:165], v[202:205], v[68:71]
	v_mfma_f32_16x16x32_f16 v[64:67], v[170:173], v[202:205], v[64:67]
	v_mfma_f32_16x16x32_f16 v[116:119], v[166:169], v[182:185], v[116:119]
	v_mfma_f32_16x16x32_f16 v[112:115], v[174:177], v[182:185], v[112:115]
	v_mfma_f32_16x16x32_f16 v[100:103], v[166:169], v[190:193], v[100:103]
	v_mfma_f32_16x16x32_f16 v[96:99], v[174:177], v[190:193], v[96:99]
	v_mfma_f32_16x16x32_f16 v[84:87], v[166:169], v[198:201], v[84:87]
	v_mfma_f32_16x16x32_f16 v[80:83], v[174:177], v[198:201], v[80:83]
	v_mfma_f32_16x16x32_f16 v[68:71], v[166:169], v[206:209], v[68:71]
	v_mfma_f32_16x16x32_f16 v[64:67], v[174:177], v[206:209], v[64:67]
	s_barrier
	s_add_i32 s18, s43, s66
	v_lshl_add_u64 v[210:211], v[210:211], 0, s[6:7]
	s_mov_b32 m0, s18
	ds_read_b128 v[178:181], v145 offset:49152
	ds_read_b128 v[182:185], v145 offset:50176
	ds_read_b128 v[186:189], v145 offset:51200
	ds_read_b128 v[190:193], v145 offset:52224
	ds_read_b128 v[194:197], v145 offset:53248
	ds_read_b128 v[198:201], v145 offset:54272
	ds_read_b128 v[202:205], v145 offset:55296
	ds_read_b128 v[206:209], v145 offset:56320
	global_load_lds_dwordx4 v[210:211], off
	s_add_i32 m0, s18, 0x2000
	s_add_u32 s16, s16, 0x40080
	v_lshl_add_u64 v[210:211], v[212:213], 0, s[6:7]
	s_addc_u32 s17, s17, 0
	s_add_i32 s18, s44, s66
	global_load_lds_dwordx4 v[210:211], off
	v_lshl_add_u64 v[210:211], s[16:17], 0, v[128:129]
	s_mov_b32 m0, s18
	s_nop 0
	global_load_lds_dwordx4 v[210:211], off
	v_lshl_add_u64 v[210:211], s[16:17], 0, v[134:135]
	s_add_i32 m0, s18, 0x2000
	s_nop 0
	global_load_lds_dwordx4 v[210:211], off
	v_lshl_add_u64 v[210:211], v[214:215], 0, s[6:7]
	s_mov_b32 m0, s36
	s_nop 0
	global_load_lds_dwordx4 v[210:211], off
	v_lshl_add_u64 v[210:211], v[216:217], 0, s[6:7]
	s_mov_b32 m0, s37
	s_nop 0
	global_load_lds_dwordx4 v[210:211], off
	s_waitcnt vmcnt(8)
	s_waitcnt lgkmcnt(0)
	s_barrier
	s_waitcnt lgkmcnt(0)
	v_mfma_f32_16x16x32_f16 v[60:63], v[146:149], v[178:181], v[60:63]
	v_mfma_f32_16x16x32_f16 v[56:59], v[154:157], v[178:181], v[56:59]
	v_mfma_f32_16x16x32_f16 v[44:47], v[146:149], v[186:189], v[44:47]
	v_mfma_f32_16x16x32_f16 v[40:43], v[154:157], v[186:189], v[40:43]
	v_mfma_f32_16x16x32_f16 v[28:31], v[146:149], v[194:197], v[28:31]
	v_mfma_f32_16x16x32_f16 v[24:27], v[154:157], v[194:197], v[24:27]
	v_mfma_f32_16x16x32_f16 v[12:15], v[146:149], v[202:205], v[12:15]
	v_mfma_f32_16x16x32_f16 v[8:11], v[154:157], v[202:205], v[8:11]
	v_mfma_f32_16x16x32_f16 v[60:63], v[150:153], v[182:185], v[60:63]
	v_mfma_f32_16x16x32_f16 v[56:59], v[158:161], v[182:185], v[56:59]
	v_mfma_f32_16x16x32_f16 v[44:47], v[150:153], v[190:193], v[44:47]
	v_mfma_f32_16x16x32_f16 v[40:43], v[158:161], v[190:193], v[40:43]
	v_mfma_f32_16x16x32_f16 v[28:31], v[150:153], v[198:201], v[28:31]
	v_mfma_f32_16x16x32_f16 v[24:27], v[158:161], v[198:201], v[24:27]
	v_mfma_f32_16x16x32_f16 v[12:15], v[150:153], v[206:209], v[12:15]
	v_mfma_f32_16x16x32_f16 v[8:11], v[158:161], v[206:209], v[8:11]
	v_mfma_f32_16x16x32_f16 v[52:55], v[162:165], v[178:181], v[52:55]
	v_mfma_f32_16x16x32_f16 v[48:51], v[170:173], v[178:181], v[48:51]
	v_mfma_f32_16x16x32_f16 v[36:39], v[162:165], v[186:189], v[36:39]
	v_mfma_f32_16x16x32_f16 v[32:35], v[170:173], v[186:189], v[32:35]
	v_mfma_f32_16x16x32_f16 v[20:23], v[162:165], v[194:197], v[20:23]
	v_mfma_f32_16x16x32_f16 v[16:19], v[170:173], v[194:197], v[16:19]
	v_mfma_f32_16x16x32_f16 v[4:7], v[162:165], v[202:205], v[4:7]
	v_mfma_f32_16x16x32_f16 v[0:3], v[170:173], v[202:205], v[0:3]
	v_mfma_f32_16x16x32_f16 v[52:55], v[166:169], v[182:185], v[52:55]
	v_mfma_f32_16x16x32_f16 v[48:51], v[174:177], v[182:185], v[48:51]
	v_mfma_f32_16x16x32_f16 v[36:39], v[166:169], v[190:193], v[36:39]
	v_mfma_f32_16x16x32_f16 v[32:35], v[174:177], v[190:193], v[32:35]
	v_mfma_f32_16x16x32_f16 v[20:23], v[166:169], v[198:201], v[20:23]
	v_mfma_f32_16x16x32_f16 v[16:19], v[174:177], v[198:201], v[16:19]
	v_mfma_f32_16x16x32_f16 v[4:7], v[166:169], v[206:209], v[4:7]
	v_mfma_f32_16x16x32_f16 v[0:3], v[174:177], v[206:209], v[0:3]
	s_barrier
	s_add_i32 s42, s42, 2
	s_add_u32 s14, s14, 0x100
	s_addc_u32 s15, s15, 0
	s_cmp_gt_u32 s42, 13

.LBB0_1328:
	v_bfe_u32 v144, v1, 4, 2
	v_and_b32_e32 v7, 15, v1
	v_lshlrev_b32_e32 v145, 4, v144
	v_lshlrev_b32_e32 v1, 2, v1
	v_or_b32_e32 v146, s54, v7
	v_lshl_or_b32 v7, v7, 6, v145
	v_and_b32_e32 v1, 32, v1
	v_bitop3_b32 v147, v7, s56, v1 bitop3:0xde
	v_lshlrev_b32_e32 v1, 14, v0
	s_add_u32 s41, s76, s26
	v_and_b32_e32 v1, 0xffff8000, v1
	s_addc_u32 s42, s77, s27
	v_lshl_add_u32 v1, v2, 11, v1
	v_and_b32_e32 v0, 1, v0
	v_lshl_or_b32 v0, v0, 6, v1
	s_add_u32 s26, s60, s26
	v_lshl_add_u32 v0, v3, 1, v0
	v_mov_b32_e32 v1, v129
	s_addc_u32 s27, s61, s27
	v_lshl_add_u64 v[136:137], s[26:27], 0, v[0:1]
	v_lshlrev_b32_e32 v0, 14, v4
	v_and_b32_e32 v0, 0xffff8000, v0
	v_lshl_add_u32 v0, v5, 11, v0
	v_and_b32_e32 v1, 1, v4
	v_lshlrev_b32_e32 v8, 6, v146
	v_lshlrev_b32_e32 v9, 2, v146
	v_lshl_or_b32 v0, v1, 6, v0
	v_and_or_b32 v8, v8, s66, v145
	v_and_b32_e32 v9, 32, v9
	s_waitcnt vmcnt(8)
	s_barrier
	s_waitcnt vmcnt(6)
	v_lshl_add_u32 v0, v6, 1, v0
	v_mov_b32_e32 v1, v129
	v_bitop3_b32 v7, v8, s55, v9 bitop3:0xde
	v_lshl_add_u64 v[138:139], s[26:27], 0, v[0:1]
	s_add_u32 s43, s62, s28
	s_addc_u32 s44, s63, 0
	s_mov_b32 s45, -2
	s_mov_b64 s[26:27], 0
	v_add_u32_e32 v148, 0, v7
	s_barrier
	s_add_u32 s28, s41, s26
	s_addc_u32 s29, s42, s27
	s_add_u32 s28, s28, 0x7a00100
	s_addc_u32 s29, s29, 0
	s_add_u32 s46, s43, s26
	s_addc_u32 s47, s44, s27
	s_add_i32 s48, 0, 0x10000
	s_cmpk_eq_i32 s26, 0x700
	s_cselect_b32 s31, s25, s29
	s_cselect_b32 s30, s24, s28
	v_add_u32_e32 v149, s48, v147
	s_cselect_b32 s29, s1, s47
	s_cselect_b32 s28, s0, s46
	s_add_i32 s49, 0, 0x14000
	ds_read_b128 v[150:153], v149
	ds_read_b128 v[154:157], v149 offset:1024
	ds_read_b128 v[158:161], v149 offset:2048
	ds_read_b128 v[162:165], v149 offset:3072
	v_add_u32_e32 v149, s49, v147
	ds_read_b128 v[166:169], v149
	ds_read_b128 v[170:173], v149 offset:1024
	ds_read_b128 v[174:177], v149 offset:2048
	ds_read_b128 v[178:181], v149 offset:3072
	v_lshl_add_u64 v[214:215], v[136:137], 0, s[26:27]
	s_add_i32 m0, s35, 0xc000
	ds_read_b128 v[182:185], v148
	ds_read_b128 v[186:189], v148 offset:1024
	ds_read_b128 v[190:193], v148 offset:2048
	ds_read_b128 v[194:197], v148 offset:3072
	ds_read_b128 v[198:201], v148 offset:4096
	ds_read_b128 v[202:205], v148 offset:5120
	ds_read_b128 v[206:209], v148 offset:6144
	ds_read_b128 v[210:213], v148 offset:7168
	global_load_lds_dwordx4 v[214:215], off
	v_lshl_add_u64 v[214:215], v[138:139], 0, s[26:27]
	s_add_i32 m0, s35, 0xe000
	s_nop 0
	global_load_lds_dwordx4 v[214:215], off
	s_waitcnt vmcnt(8)
	s_waitcnt lgkmcnt(0)
	s_barrier
	s_waitcnt lgkmcnt(0)
	v_mfma_f32_16x16x32_f16 v[124:127], v[150:153], v[182:185], 0
	v_mfma_f32_16x16x32_f16 v[120:123], v[158:161], v[182:185], 0
	v_mfma_f32_16x16x32_f16 v[108:111], v[150:153], v[190:193], 0
	v_mfma_f32_16x16x32_f16 v[104:107], v[158:161], v[190:193], 0
	v_mfma_f32_16x16x32_f16 v[92:95], v[150:153], v[198:201], 0
	v_mfma_f32_16x16x32_f16 v[88:91], v[158:161], v[198:201], 0
	v_mfma_f32_16x16x32_f16 v[76:79], v[150:153], v[206:209], 0
	v_mfma_f32_16x16x32_f16 v[72:75], v[158:161], v[206:209], 0
	v_mfma_f32_16x16x32_f16 v[124:127], v[154:157], v[186:189], v[124:127]
	v_mfma_f32_16x16x32_f16 v[120:123], v[162:165], v[186:189], v[120:123]
	v_mfma_f32_16x16x32_f16 v[108:111], v[154:157], v[194:197], v[108:111]
	v_mfma_f32_16x16x32_f16 v[104:107], v[162:165], v[194:197], v[104:107]
	v_mfma_f32_16x16x32_f16 v[92:95], v[154:157], v[202:205], v[92:95]
	v_mfma_f32_16x16x32_f16 v[88:91], v[162:165], v[202:205], v[88:91]
	v_mfma_f32_16x16x32_f16 v[76:79], v[154:157], v[210:213], v[76:79]
	v_mfma_f32_16x16x32_f16 v[72:75], v[162:165], v[210:213], v[72:75]
	v_mfma_f32_16x16x32_f16 v[116:119], v[166:169], v[182:185], 0
	v_mfma_f32_16x16x32_f16 v[112:115], v[174:177], v[182:185], 0
	v_mfma_f32_16x16x32_f16 v[100:103], v[166:169], v[190:193], 0
	v_mfma_f32_16x16x32_f16 v[96:99], v[174:177], v[190:193], 0
	v_mfma_f32_16x16x32_f16 v[84:87], v[166:169], v[198:201], 0
	v_mfma_f32_16x16x32_f16 v[80:83], v[174:177], v[198:201], 0
	v_mfma_f32_16x16x32_f16 v[68:71], v[166:169], v[206:209], 0
	v_mfma_f32_16x16x32_f16 v[64:67], v[174:177], v[206:209], 0
	v_mfma_f32_16x16x32_f16 v[116:119], v[170:173], v[186:189], v[116:119]
	v_mfma_f32_16x16x32_f16 v[112:115], v[178:181], v[186:189], v[112:115]
	v_mfma_f32_16x16x32_f16 v[100:103], v[170:173], v[194:197], v[100:103]
	v_mfma_f32_16x16x32_f16 v[96:99], v[178:181], v[194:197], v[96:99]
	v_mfma_f32_16x16x32_f16 v[84:87], v[170:173], v[202:205], v[84:87]
	v_mfma_f32_16x16x32_f16 v[80:83], v[178:181], v[202:205], v[80:83]
	v_mfma_f32_16x16x32_f16 v[68:71], v[170:173], v[210:213], v[68:71]
	v_mfma_f32_16x16x32_f16 v[64:67], v[178:181], v[210:213], v[64:67]
	s_barrier
	s_add_i32 s46, s48, s53
	v_lshl_add_u64 v[214:215], s[28:29], 0, v[128:129]
	s_mov_b32 m0, s46
	ds_read_b128 v[182:185], v148 offset:16384
	ds_read_b128 v[186:189], v148 offset:17408
	ds_read_b128 v[190:193], v148 offset:18432
	ds_read_b128 v[194:197], v148 offset:19456
	ds_read_b128 v[198:201], v148 offset:20480
	ds_read_b128 v[202:205], v148 offset:21504
	ds_read_b128 v[206:209], v148 offset:22528
	ds_read_b128 v[210:213], v148 offset:23552
	global_load_lds_dwordx4 v[214:215], off
	s_add_i32 m0, s46, 0x2000
	s_add_u32 s46, s28, 0x40000
	v_lshl_add_u64 v[216:217], s[28:29], 0, v[134:135]
	s_addc_u32 s47, s29, 0
	s_add_i32 s48, s49, s53
	global_load_lds_dwordx4 v[216:217], off
	v_lshl_add_u64 v[218:219], s[46:47], 0, v[128:129]
	s_mov_b32 m0, s48
	v_lshl_add_u64 v[220:221], s[30:31], 0, v[132:133]
	global_load_lds_dwordx4 v[218:219], off
	v_lshl_add_u64 v[218:219], s[46:47], 0, v[134:135]
	s_add_i32 m0, s48, 0x2000
	s_nop 0
	global_load_lds_dwordx4 v[218:219], off
	v_lshl_add_u64 v[218:219], s[30:31], 0, v[130:131]
	s_mov_b32 m0, s35
	s_nop 0
	global_load_lds_dwordx4 v[218:219], off
	s_mov_b32 m0, s36
	s_nop 0
	global_load_lds_dwordx4 v[220:221], off
	s_waitcnt vmcnt(8)
	s_waitcnt lgkmcnt(0)
	s_barrier
	s_waitcnt lgkmcnt(0)
	v_mfma_f32_16x16x32_f16 v[60:63], v[150:153], v[182:185], 0
	v_mfma_f32_16x16x32_f16 v[56:59], v[158:161], v[182:185], 0
	v_mfma_f32_16x16x32_f16 v[44:47], v[150:153], v[190:193], 0
	v_mfma_f32_16x16x32_f16 v[40:43], v[158:161], v[190:193], 0
	v_mfma_f32_16x16x32_f16 v[28:31], v[150:153], v[198:201], 0
	v_mfma_f32_16x16x32_f16 v[24:27], v[158:161], v[198:201], 0
	v_mfma_f32_16x16x32_f16 v[12:15], v[150:153], v[206:209], 0
	v_mfma_f32_16x16x32_f16 v[8:11], v[158:161], v[206:209], 0
	v_mfma_f32_16x16x32_f16 v[60:63], v[154:157], v[186:189], v[60:63]
	v_mfma_f32_16x16x32_f16 v[56:59], v[162:165], v[186:189], v[56:59]
	v_mfma_f32_16x16x32_f16 v[44:47], v[154:157], v[194:197], v[44:47]
	v_mfma_f32_16x16x32_f16 v[40:43], v[162:165], v[194:197], v[40:43]
	v_mfma_f32_16x16x32_f16 v[28:31], v[154:157], v[202:205], v[28:31]
	v_mfma_f32_16x16x32_f16 v[24:27], v[162:165], v[202:205], v[24:27]
	v_mfma_f32_16x16x32_f16 v[12:15], v[154:157], v[210:213], v[12:15]
	v_mfma_f32_16x16x32_f16 v[8:11], v[162:165], v[210:213], v[8:11]
	v_mfma_f32_16x16x32_f16 v[52:55], v[166:169], v[182:185], 0
	v_mfma_f32_16x16x32_f16 v[48:51], v[174:177], v[182:185], 0
	v_mfma_f32_16x16x32_f16 v[36:39], v[166:169], v[190:193], 0
	v_mfma_f32_16x16x32_f16 v[32:35], v[174:177], v[190:193], 0
	v_mfma_f32_16x16x32_f16 v[20:23], v[166:169], v[198:201], 0
	v_mfma_f32_16x16x32_f16 v[16:19], v[174:177], v[198:201], 0
	v_mfma_f32_16x16x32_f16 v[4:7], v[166:169], v[206:209], 0
	v_mfma_f32_16x16x32_f16 v[0:3], v[174:177], v[206:209], 0
	v_mfma_f32_16x16x32_f16 v[52:55], v[170:173], v[186:189], v[52:55]
	v_mfma_f32_16x16x32_f16 v[48:51], v[178:181], v[186:189], v[48:51]
	v_mfma_f32_16x16x32_f16 v[36:39], v[170:173], v[194:197], v[36:39]
	v_mfma_f32_16x16x32_f16 v[32:35], v[178:181], v[194:197], v[32:35]
	v_mfma_f32_16x16x32_f16 v[20:23], v[170:173], v[202:205], v[20:23]
	v_mfma_f32_16x16x32_f16 v[16:19], v[178:181], v[202:205], v[16:19]
	v_mfma_f32_16x16x32_f16 v[4:7], v[170:173], v[210:213], v[4:7]
	v_mfma_f32_16x16x32_f16 v[0:3], v[178:181], v[210:213], v[0:3]
	s_barrier
	s_add_i32 s46, 0, 0x18000
	v_add_u32_e32 v149, s46, v147
	s_add_i32 s47, 0, 0x1c000
	ds_read_b128 v[150:153], v149
	ds_read_b128 v[154:157], v149 offset:1024
	ds_read_b128 v[158:161], v149 offset:2048
	ds_read_b128 v[162:165], v149 offset:3072
	v_add_u32_e32 v149, s47, v147
	ds_read_b128 v[166:169], v149
	ds_read_b128 v[170:173], v149 offset:1024
	ds_read_b128 v[174:177], v149 offset:2048
	ds_read_b128 v[178:181], v149 offset:3072
	s_add_u32 s30, s30, 0x40000
	s_addc_u32 s31, s31, 0
	s_mov_b32 m0, s37
	v_lshl_add_u64 v[222:223], s[30:31], 0, v[130:131]
	ds_read_b128 v[182:185], v148 offset:32768
	ds_read_b128 v[186:189], v148 offset:33792
	ds_read_b128 v[190:193], v148 offset:34816
	ds_read_b128 v[194:197], v148 offset:35840
	ds_read_b128 v[198:201], v148 offset:36864
	ds_read_b128 v[202:205], v148 offset:37888
	ds_read_b128 v[206:209], v148 offset:38912
	ds_read_b128 v[210:213], v148 offset:39936
	global_load_lds_dwordx4 v[222:223], off
	v_lshl_add_u64 v[222:223], s[30:31], 0, v[132:133]
	s_mov_b32 m0, s38
	s_nop 0
	global_load_lds_dwordx4 v[222:223], off
	s_waitcnt vmcnt(8)
	s_waitcnt lgkmcnt(0)
	s_barrier
	s_waitcnt lgkmcnt(0)
	v_mfma_f32_16x16x32_f16 v[124:127], v[150:153], v[182:185], v[124:127]
	v_mfma_f32_16x16x32_f16 v[120:123], v[158:161], v[182:185], v[120:123]
	v_mfma_f32_16x16x32_f16 v[108:111], v[150:153], v[190:193], v[108:111]
	v_mfma_f32_16x16x32_f16 v[104:107], v[158:161], v[190:193], v[104:107]
	v_mfma_f32_16x16x32_f16 v[92:95], v[150:153], v[198:201], v[92:95]
	v_mfma_f32_16x16x32_f16 v[88:91], v[158:161], v[198:201], v[88:91]
	v_mfma_f32_16x16x32_f16 v[76:79], v[150:153], v[206:209], v[76:79]
	v_mfma_f32_16x16x32_f16 v[72:75], v[158:161], v[206:209], v[72:75]
	v_mfma_f32_16x16x32_f16 v[124:127], v[154:157], v[186:189], v[124:127]
	v_mfma_f32_16x16x32_f16 v[120:123], v[162:165], v[186:189], v[120:123]
	v_mfma_f32_16x16x32_f16 v[108:111], v[154:157], v[194:197], v[108:111]
	v_mfma_f32_16x16x32_f16 v[104:107], v[162:165], v[194:197], v[104:107]
	v_mfma_f32_16x16x32_f16 v[92:95], v[154:157], v[202:205], v[92:95]
	v_mfma_f32_16x16x32_f16 v[88:91], v[162:165], v[202:205], v[88:91]
	v_mfma_f32_16x16x32_f16 v[76:79], v[154:157], v[210:213], v[76:79]
	v_mfma_f32_16x16x32_f16 v[72:75], v[162:165], v[210:213], v[72:75]
	v_mfma_f32_16x16x32_f16 v[116:119], v[166:169], v[182:185], v[116:119]
	v_mfma_f32_16x16x32_f16 v[112:115], v[174:177], v[182:185], v[112:115]
	v_mfma_f32_16x16x32_f16 v[100:103], v[166:169], v[190:193], v[100:103]
	v_mfma_f32_16x16x32_f16 v[96:99], v[174:177], v[190:193], v[96:99]
	v_mfma_f32_16x16x32_f16 v[84:87], v[166:169], v[198:201], v[84:87]
	v_mfma_f32_16x16x32_f16 v[80:83], v[174:177], v[198:201], v[80:83]
	v_mfma_f32_16x16x32_f16 v[68:71], v[166:169], v[206:209], v[68:71]
	v_mfma_f32_16x16x32_f16 v[64:67], v[174:177], v[206:209], v[64:67]
	v_mfma_f32_16x16x32_f16 v[116:119], v[170:173], v[186:189], v[116:119]
	v_mfma_f32_16x16x32_f16 v[112:115], v[178:181], v[186:189], v[112:115]
	v_mfma_f32_16x16x32_f16 v[100:103], v[170:173], v[194:197], v[100:103]
	v_mfma_f32_16x16x32_f16 v[96:99], v[178:181], v[194:197], v[96:99]
	v_mfma_f32_16x16x32_f16 v[84:87], v[170:173], v[202:205], v[84:87]
	v_mfma_f32_16x16x32_f16 v[80:83], v[178:181], v[202:205], v[80:83]
	v_mfma_f32_16x16x32_f16 v[68:71], v[170:173], v[210:213], v[68:71]
	v_mfma_f32_16x16x32_f16 v[64:67], v[178:181], v[210:213], v[64:67]
	s_barrier
	s_add_i32 s30, s46, s53
	v_lshl_add_u64 v[214:215], v[214:215], 0, s[20:21]
	s_mov_b32 m0, s30
	ds_read_b128 v[182:185], v148 offset:49152
	ds_read_b128 v[186:189], v148 offset:50176
	ds_read_b128 v[190:193], v148 offset:51200
	ds_read_b128 v[194:197], v148 offset:52224
	ds_read_b128 v[198:201], v148 offset:53248
	ds_read_b128 v[202:205], v148 offset:54272
	ds_read_b128 v[206:209], v148 offset:55296
	ds_read_b128 v[210:213], v148 offset:56320
	global_load_lds_dwordx4 v[214:215], off
	s_add_i32 m0, s30, 0x2000
	s_add_u32 s28, s28, 0x40080
	v_lshl_add_u64 v[214:215], v[216:217], 0, s[20:21]
	s_addc_u32 s29, s29, 0
	s_add_i32 s30, s47, s53
	global_load_lds_dwordx4 v[214:215], off
	v_lshl_add_u64 v[214:215], s[28:29], 0, v[128:129]
	s_mov_b32 m0, s30
	s_nop 0
	global_load_lds_dwordx4 v[214:215], off
	v_lshl_add_u64 v[214:215], s[28:29], 0, v[134:135]
	s_add_i32 m0, s30, 0x2000
	s_nop 0
	global_load_lds_dwordx4 v[214:215], off
	v_lshl_add_u64 v[214:215], v[218:219], 0, s[20:21]
	s_mov_b32 m0, s39
	s_nop 0
	global_load_lds_dwordx4 v[214:215], off
	v_lshl_add_u64 v[214:215], v[220:221], 0, s[20:21]
	s_mov_b32 m0, s40
	s_nop 0
	global_load_lds_dwordx4 v[214:215], off
	s_waitcnt vmcnt(8)
	s_waitcnt lgkmcnt(0)
	s_barrier
	s_waitcnt lgkmcnt(0)
	v_mfma_f32_16x16x32_f16 v[60:63], v[150:153], v[182:185], v[60:63]
	v_mfma_f32_16x16x32_f16 v[56:59], v[158:161], v[182:185], v[56:59]
	v_mfma_f32_16x16x32_f16 v[44:47], v[150:153], v[190:193], v[44:47]
	v_mfma_f32_16x16x32_f16 v[40:43], v[158:161], v[190:193], v[40:43]
	v_mfma_f32_16x16x32_f16 v[28:31], v[150:153], v[198:201], v[28:31]
	v_mfma_f32_16x16x32_f16 v[24:27], v[158:161], v[198:201], v[24:27]
	v_mfma_f32_16x16x32_f16 v[12:15], v[150:153], v[206:209], v[12:15]
	v_mfma_f32_16x16x32_f16 v[8:11], v[158:161], v[206:209], v[8:11]
	v_mfma_f32_16x16x32_f16 v[60:63], v[154:157], v[186:189], v[60:63]
	v_mfma_f32_16x16x32_f16 v[56:59], v[162:165], v[186:189], v[56:59]
	v_mfma_f32_16x16x32_f16 v[44:47], v[154:157], v[194:197], v[44:47]
	v_mfma_f32_16x16x32_f16 v[40:43], v[162:165], v[194:197], v[40:43]
	v_mfma_f32_16x16x32_f16 v[28:31], v[154:157], v[202:205], v[28:31]
	v_mfma_f32_16x16x32_f16 v[24:27], v[162:165], v[202:205], v[24:27]
	v_mfma_f32_16x16x32_f16 v[12:15], v[154:157], v[210:213], v[12:15]
	v_mfma_f32_16x16x32_f16 v[8:11], v[162:165], v[210:213], v[8:11]
	v_mfma_f32_16x16x32_f16 v[52:55], v[166:169], v[182:185], v[52:55]
	v_mfma_f32_16x16x32_f16 v[48:51], v[174:177], v[182:185], v[48:51]
	v_mfma_f32_16x16x32_f16 v[36:39], v[166:169], v[190:193], v[36:39]
	v_mfma_f32_16x16x32_f16 v[32:35], v[174:177], v[190:193], v[32:35]
	v_mfma_f32_16x16x32_f16 v[20:23], v[166:169], v[198:201], v[20:23]
	v_mfma_f32_16x16x32_f16 v[16:19], v[174:177], v[198:201], v[16:19]
	v_mfma_f32_16x16x32_f16 v[4:7], v[166:169], v[206:209], v[4:7]
	v_mfma_f32_16x16x32_f16 v[0:3], v[174:177], v[206:209], v[0:3]
	v_mfma_f32_16x16x32_f16 v[52:55], v[170:173], v[186:189], v[52:55]
	v_mfma_f32_16x16x32_f16 v[48:51], v[178:181], v[186:189], v[48:51]
	v_mfma_f32_16x16x32_f16 v[36:39], v[170:173], v[194:197], v[36:39]
	v_mfma_f32_16x16x32_f16 v[32:35], v[178:181], v[194:197], v[32:35]
	v_mfma_f32_16x16x32_f16 v[20:23], v[170:173], v[202:205], v[20:23]
	v_mfma_f32_16x16x32_f16 v[16:19], v[178:181], v[202:205], v[16:19]
	v_mfma_f32_16x16x32_f16 v[4:7], v[170:173], v[210:213], v[4:7]
	v_mfma_f32_16x16x32_f16 v[0:3], v[178:181], v[210:213], v[0:3]
	s_barrier
	s_add_i32 s45, s45, 2
	s_add_u32 s26, s26, 0x100
	s_addc_u32 s27, s27, 0
	s_cmp_gt_u32 s45, 13

.LBB0_1428:
	s_add_u32 s22, s22, 0x40080
	s_addc_u32 s23, s23, 0
	s_add_u32 s13, s30, 0x100
	s_addc_u32 s15, s31, 0
	s_mov_b32 s51, -2
	ds_read_b128 v[158:161], v151
	ds_read_b128 v[162:165], v151 offset:1024
	ds_read_b128 v[166:169], v151 offset:2048
	ds_read_b128 v[170:173], v151 offset:3072
	ds_read_b128 v[174:177], v152
	ds_read_b128 v[178:181], v152 offset:1024
	ds_read_b128 v[182:185], v152 offset:2048
	ds_read_b128 v[186:189], v152 offset:3072
	s_add_u32 s30, s22, 0xfffc0080
	s_addc_u32 s31, s23, -1
	s_cmp_eq_u32 s51, 12
	s_cselect_b32 s35, s17, s31
	s_cselect_b32 s34, s16, s30
	s_cselect_b32 s31, s19, s15
	s_cselect_b32 s30, s18, s13
	v_lshl_add_u64 v[222:223], s[22:23], 0, v[138:139]
	s_add_i32 m0, s21, 0xc000
	ds_read_b128 v[190:193], v153
	ds_read_b128 v[194:197], v153 offset:1024
	ds_read_b128 v[198:201], v153 offset:2048
	ds_read_b128 v[202:205], v153 offset:3072
	ds_read_b128 v[206:209], v153 offset:4096
	ds_read_b128 v[210:213], v153 offset:5120
	ds_read_b128 v[214:217], v153 offset:6144
	ds_read_b128 v[218:221], v153 offset:7168
	global_load_lds_dwordx4 v[222:223], off
	v_lshl_add_u64 v[222:223], s[22:23], 0, v[140:141]
	s_add_i32 m0, s21, 0xe000
	s_nop 0
	global_load_lds_dwordx4 v[222:223], off
	s_waitcnt vmcnt(8)
	s_waitcnt lgkmcnt(0)
	s_barrier
	s_waitcnt lgkmcnt(0)
	v_mfma_f32_16x16x32_f16 v[124:127], v[158:161], v[190:193], 0
	v_mfma_f32_16x16x32_f16 v[120:123], v[166:169], v[190:193], 0
	v_mfma_f32_16x16x32_f16 v[108:111], v[158:161], v[198:201], 0
	v_mfma_f32_16x16x32_f16 v[104:107], v[166:169], v[198:201], 0
	v_mfma_f32_16x16x32_f16 v[92:95], v[158:161], v[206:209], 0
	v_mfma_f32_16x16x32_f16 v[88:91], v[166:169], v[206:209], 0
	v_mfma_f32_16x16x32_f16 v[76:79], v[158:161], v[214:217], 0
	v_mfma_f32_16x16x32_f16 v[72:75], v[166:169], v[214:217], 0
	v_mfma_f32_16x16x32_f16 v[124:127], v[162:165], v[194:197], v[124:127]
	v_mfma_f32_16x16x32_f16 v[120:123], v[170:173], v[194:197], v[120:123]
	v_mfma_f32_16x16x32_f16 v[108:111], v[162:165], v[202:205], v[108:111]
	v_mfma_f32_16x16x32_f16 v[104:107], v[170:173], v[202:205], v[104:107]
	v_mfma_f32_16x16x32_f16 v[92:95], v[162:165], v[210:213], v[92:95]
	v_mfma_f32_16x16x32_f16 v[88:91], v[170:173], v[210:213], v[88:91]
	v_mfma_f32_16x16x32_f16 v[76:79], v[162:165], v[218:221], v[76:79]
	v_mfma_f32_16x16x32_f16 v[72:75], v[170:173], v[218:221], v[72:75]
	v_mfma_f32_16x16x32_f16 v[116:119], v[174:177], v[190:193], 0
	v_mfma_f32_16x16x32_f16 v[112:115], v[182:185], v[190:193], 0
	v_mfma_f32_16x16x32_f16 v[100:103], v[174:177], v[198:201], 0
	v_mfma_f32_16x16x32_f16 v[96:99], v[182:185], v[198:201], 0
	v_mfma_f32_16x16x32_f16 v[84:87], v[174:177], v[206:209], 0
	v_mfma_f32_16x16x32_f16 v[80:83], v[182:185], v[206:209], 0
	v_mfma_f32_16x16x32_f16 v[68:71], v[174:177], v[214:217], 0
	v_mfma_f32_16x16x32_f16 v[64:67], v[182:185], v[214:217], 0
	v_mfma_f32_16x16x32_f16 v[116:119], v[178:181], v[194:197], v[116:119]
	v_mfma_f32_16x16x32_f16 v[112:115], v[186:189], v[194:197], v[112:115]
	v_mfma_f32_16x16x32_f16 v[100:103], v[178:181], v[202:205], v[100:103]
	v_mfma_f32_16x16x32_f16 v[96:99], v[186:189], v[202:205], v[96:99]
	v_mfma_f32_16x16x32_f16 v[84:87], v[178:181], v[210:213], v[84:87]
	v_mfma_f32_16x16x32_f16 v[80:83], v[186:189], v[210:213], v[80:83]
	v_mfma_f32_16x16x32_f16 v[68:71], v[178:181], v[218:221], v[68:71]
	v_mfma_f32_16x16x32_f16 v[64:67], v[186:189], v[218:221], v[64:67]
	s_barrier
	s_add_i32 s52, s46, s3
	v_lshl_add_u64 v[222:223], s[30:31], 0, v[132:133]
	s_mov_b32 m0, s52
	ds_read_b128 v[190:193], v153 offset:16384
	ds_read_b128 v[194:197], v153 offset:17408
	ds_read_b128 v[198:201], v153 offset:18432
	ds_read_b128 v[202:205], v153 offset:19456
	ds_read_b128 v[206:209], v153 offset:20480
	ds_read_b128 v[210:213], v153 offset:21504
	ds_read_b128 v[214:217], v153 offset:22528
	ds_read_b128 v[218:221], v153 offset:23552
	global_load_lds_dwordx4 v[222:223], off
	s_add_i32 m0, s52, 0x2000
	s_add_u32 s52, s30, 0x40000
	v_lshl_add_u64 v[224:225], s[30:31], 0, v[128:129]
	s_addc_u32 s53, s31, 0
	s_add_i32 s54, s47, s3
	global_load_lds_dwordx4 v[224:225], off
	v_lshl_add_u64 v[226:227], s[52:53], 0, v[132:133]
	s_mov_b32 m0, s54
	v_lshl_add_u64 v[228:229], s[34:35], 0, v[130:131]
	global_load_lds_dwordx4 v[226:227], off
	v_lshl_add_u64 v[226:227], s[52:53], 0, v[128:129]
	s_add_i32 m0, s54, 0x2000
	s_nop 0
	global_load_lds_dwordx4 v[226:227], off
	v_lshl_add_u64 v[226:227], s[34:35], 0, v[134:135]
	s_mov_b32 m0, s21
	s_nop 0
	global_load_lds_dwordx4 v[226:227], off
	s_mov_b32 m0, s40
	s_nop 0
	global_load_lds_dwordx4 v[228:229], off
	s_waitcnt vmcnt(8)
	s_waitcnt lgkmcnt(0)
	s_barrier
	s_waitcnt lgkmcnt(0)
	v_mfma_f32_16x16x32_f16 v[60:63], v[158:161], v[190:193], 0
	v_mfma_f32_16x16x32_f16 v[56:59], v[166:169], v[190:193], 0
	v_mfma_f32_16x16x32_f16 v[44:47], v[158:161], v[198:201], 0
	v_mfma_f32_16x16x32_f16 v[40:43], v[166:169], v[198:201], 0
	v_mfma_f32_16x16x32_f16 v[28:31], v[158:161], v[206:209], 0
	v_mfma_f32_16x16x32_f16 v[24:27], v[166:169], v[206:209], 0
	v_mfma_f32_16x16x32_f16 v[12:15], v[158:161], v[214:217], 0
	v_mfma_f32_16x16x32_f16 v[8:11], v[166:169], v[214:217], 0
	v_mfma_f32_16x16x32_f16 v[60:63], v[162:165], v[194:197], v[60:63]
	v_mfma_f32_16x16x32_f16 v[56:59], v[170:173], v[194:197], v[56:59]
	v_mfma_f32_16x16x32_f16 v[44:47], v[162:165], v[202:205], v[44:47]
	v_mfma_f32_16x16x32_f16 v[40:43], v[170:173], v[202:205], v[40:43]
	v_mfma_f32_16x16x32_f16 v[28:31], v[162:165], v[210:213], v[28:31]
	v_mfma_f32_16x16x32_f16 v[24:27], v[170:173], v[210:213], v[24:27]
	v_mfma_f32_16x16x32_f16 v[12:15], v[162:165], v[218:221], v[12:15]
	v_mfma_f32_16x16x32_f16 v[8:11], v[170:173], v[218:221], v[8:11]
	v_mfma_f32_16x16x32_f16 v[52:55], v[174:177], v[190:193], 0
	v_mfma_f32_16x16x32_f16 v[48:51], v[182:185], v[190:193], 0
	v_mfma_f32_16x16x32_f16 v[36:39], v[174:177], v[198:201], 0
	v_mfma_f32_16x16x32_f16 v[32:35], v[182:185], v[198:201], 0
	v_mfma_f32_16x16x32_f16 v[20:23], v[174:177], v[206:209], 0
	v_mfma_f32_16x16x32_f16 v[16:19], v[182:185], v[206:209], 0
	v_mfma_f32_16x16x32_f16 v[4:7], v[174:177], v[214:217], 0
	v_mfma_f32_16x16x32_f16 v[0:3], v[182:185], v[214:217], 0
	v_mfma_f32_16x16x32_f16 v[52:55], v[178:181], v[194:197], v[52:55]
	v_mfma_f32_16x16x32_f16 v[48:51], v[186:189], v[194:197], v[48:51]
	v_mfma_f32_16x16x32_f16 v[36:39], v[178:181], v[202:205], v[36:39]
	v_mfma_f32_16x16x32_f16 v[32:35], v[186:189], v[202:205], v[32:35]
	v_mfma_f32_16x16x32_f16 v[20:23], v[178:181], v[210:213], v[20:23]
	v_mfma_f32_16x16x32_f16 v[16:19], v[186:189], v[210:213], v[16:19]
	v_mfma_f32_16x16x32_f16 v[4:7], v[178:181], v[218:221], v[4:7]
	v_mfma_f32_16x16x32_f16 v[0:3], v[186:189], v[218:221], v[0:3]
	s_barrier
	ds_read_b128 v[158:161], v154
	ds_read_b128 v[162:165], v154 offset:1024
	ds_read_b128 v[166:169], v154 offset:2048
	ds_read_b128 v[170:173], v154 offset:3072
	ds_read_b128 v[174:177], v155
	ds_read_b128 v[178:181], v155 offset:1024
	ds_read_b128 v[182:185], v155 offset:2048
	ds_read_b128 v[186:189], v155 offset:3072
	s_add_u32 s34, s34, 0x40000
	s_addc_u32 s35, s35, 0
	s_mov_b32 m0, s41
	v_lshl_add_u64 v[230:231], s[34:35], 0, v[134:135]
	ds_read_b128 v[190:193], v153 offset:32768
	ds_read_b128 v[194:197], v153 offset:33792
	ds_read_b128 v[198:201], v153 offset:34816
	ds_read_b128 v[202:205], v153 offset:35840
	ds_read_b128 v[206:209], v153 offset:36864
	ds_read_b128 v[210:213], v153 offset:37888
	ds_read_b128 v[214:217], v153 offset:38912
	ds_read_b128 v[218:221], v153 offset:39936
	global_load_lds_dwordx4 v[230:231], off
	v_lshl_add_u64 v[230:231], s[34:35], 0, v[130:131]
	s_mov_b32 m0, s42
	s_nop 0
	global_load_lds_dwordx4 v[230:231], off
	s_waitcnt vmcnt(8)
	s_waitcnt lgkmcnt(0)
	s_barrier
	s_waitcnt lgkmcnt(0)
	v_mfma_f32_16x16x32_f16 v[124:127], v[158:161], v[190:193], v[124:127]
	v_mfma_f32_16x16x32_f16 v[120:123], v[166:169], v[190:193], v[120:123]
	v_mfma_f32_16x16x32_f16 v[108:111], v[158:161], v[198:201], v[108:111]
	v_mfma_f32_16x16x32_f16 v[104:107], v[166:169], v[198:201], v[104:107]
	v_mfma_f32_16x16x32_f16 v[92:95], v[158:161], v[206:209], v[92:95]
	v_mfma_f32_16x16x32_f16 v[88:91], v[166:169], v[206:209], v[88:91]
	v_mfma_f32_16x16x32_f16 v[76:79], v[158:161], v[214:217], v[76:79]
	v_mfma_f32_16x16x32_f16 v[72:75], v[166:169], v[214:217], v[72:75]
	v_mfma_f32_16x16x32_f16 v[124:127], v[162:165], v[194:197], v[124:127]
	v_mfma_f32_16x16x32_f16 v[120:123], v[170:173], v[194:197], v[120:123]
	v_mfma_f32_16x16x32_f16 v[108:111], v[162:165], v[202:205], v[108:111]
	v_mfma_f32_16x16x32_f16 v[104:107], v[170:173], v[202:205], v[104:107]
	v_mfma_f32_16x16x32_f16 v[92:95], v[162:165], v[210:213], v[92:95]
	v_mfma_f32_16x16x32_f16 v[88:91], v[170:173], v[210:213], v[88:91]
	v_mfma_f32_16x16x32_f16 v[76:79], v[162:165], v[218:221], v[76:79]
	v_mfma_f32_16x16x32_f16 v[72:75], v[170:173], v[218:221], v[72:75]
	v_mfma_f32_16x16x32_f16 v[116:119], v[174:177], v[190:193], v[116:119]
	v_mfma_f32_16x16x32_f16 v[112:115], v[182:185], v[190:193], v[112:115]
	v_mfma_f32_16x16x32_f16 v[100:103], v[174:177], v[198:201], v[100:103]
	v_mfma_f32_16x16x32_f16 v[96:99], v[182:185], v[198:201], v[96:99]
	v_mfma_f32_16x16x32_f16 v[84:87], v[174:177], v[206:209], v[84:87]
	v_mfma_f32_16x16x32_f16 v[80:83], v[182:185], v[206:209], v[80:83]
	v_mfma_f32_16x16x32_f16 v[68:71], v[174:177], v[214:217], v[68:71]
	v_mfma_f32_16x16x32_f16 v[64:67], v[182:185], v[214:217], v[64:67]
	v_mfma_f32_16x16x32_f16 v[116:119], v[178:181], v[194:197], v[116:119]
	v_mfma_f32_16x16x32_f16 v[112:115], v[186:189], v[194:197], v[112:115]
	v_mfma_f32_16x16x32_f16 v[100:103], v[178:181], v[202:205], v[100:103]
	v_mfma_f32_16x16x32_f16 v[96:99], v[186:189], v[202:205], v[96:99]
	v_mfma_f32_16x16x32_f16 v[84:87], v[178:181], v[210:213], v[84:87]
	v_mfma_f32_16x16x32_f16 v[80:83], v[186:189], v[210:213], v[80:83]
	v_mfma_f32_16x16x32_f16 v[68:71], v[178:181], v[218:221], v[68:71]
	v_mfma_f32_16x16x32_f16 v[64:67], v[186:189], v[218:221], v[64:67]
	s_barrier
	s_add_i32 s34, s48, s3
	v_lshl_add_u64 v[222:223], v[222:223], 0, s[10:11]
	s_mov_b32 m0, s34
	ds_read_b128 v[190:193], v153 offset:49152
	ds_read_b128 v[194:197], v153 offset:50176
	ds_read_b128 v[198:201], v153 offset:51200
	ds_read_b128 v[202:205], v153 offset:52224
	ds_read_b128 v[206:209], v153 offset:53248
	ds_read_b128 v[210:213], v153 offset:54272
	ds_read_b128 v[214:217], v153 offset:55296
	ds_read_b128 v[218:221], v153 offset:56320
	global_load_lds_dwordx4 v[222:223], off
	s_add_i32 m0, s34, 0x2000
	s_add_u32 s30, s30, 0x40080
	v_lshl_add_u64 v[222:223], v[224:225], 0, s[10:11]
	s_addc_u32 s31, s31, 0
	s_add_i32 s34, s49, s3
	global_load_lds_dwordx4 v[222:223], off
	v_lshl_add_u64 v[222:223], s[30:31], 0, v[132:133]
	s_mov_b32 m0, s34
	s_nop 0
	global_load_lds_dwordx4 v[222:223], off
	v_lshl_add_u64 v[222:223], s[30:31], 0, v[128:129]
	s_add_i32 m0, s34, 0x2000
	s_nop 0
	global_load_lds_dwordx4 v[222:223], off
	v_lshl_add_u64 v[222:223], v[226:227], 0, s[10:11]
	s_mov_b32 m0, s43
	s_nop 0
	global_load_lds_dwordx4 v[222:223], off
	v_lshl_add_u64 v[222:223], v[228:229], 0, s[10:11]
	s_mov_b32 m0, s44
	s_nop 0
	global_load_lds_dwordx4 v[222:223], off
	s_waitcnt vmcnt(8)
	s_waitcnt lgkmcnt(0)
	s_barrier
	s_waitcnt lgkmcnt(0)
	v_mfma_f32_16x16x32_f16 v[60:63], v[158:161], v[190:193], v[60:63]
	v_mfma_f32_16x16x32_f16 v[56:59], v[166:169], v[190:193], v[56:59]
	v_mfma_f32_16x16x32_f16 v[44:47], v[158:161], v[198:201], v[44:47]
	v_mfma_f32_16x16x32_f16 v[40:43], v[166:169], v[198:201], v[40:43]
	v_mfma_f32_16x16x32_f16 v[28:31], v[158:161], v[206:209], v[28:31]
	v_mfma_f32_16x16x32_f16 v[24:27], v[166:169], v[206:209], v[24:27]
	v_mfma_f32_16x16x32_f16 v[12:15], v[158:161], v[214:217], v[12:15]
	v_mfma_f32_16x16x32_f16 v[8:11], v[166:169], v[214:217], v[8:11]
	v_mfma_f32_16x16x32_f16 v[60:63], v[162:165], v[194:197], v[60:63]
	v_mfma_f32_16x16x32_f16 v[56:59], v[170:173], v[194:197], v[56:59]
	v_mfma_f32_16x16x32_f16 v[44:47], v[162:165], v[202:205], v[44:47]
	v_mfma_f32_16x16x32_f16 v[40:43], v[170:173], v[202:205], v[40:43]
	v_mfma_f32_16x16x32_f16 v[28:31], v[162:165], v[210:213], v[28:31]
	v_mfma_f32_16x16x32_f16 v[24:27], v[170:173], v[210:213], v[24:27]
	v_mfma_f32_16x16x32_f16 v[12:15], v[162:165], v[218:221], v[12:15]
	v_mfma_f32_16x16x32_f16 v[8:11], v[170:173], v[218:221], v[8:11]
	v_mfma_f32_16x16x32_f16 v[52:55], v[174:177], v[190:193], v[52:55]
	v_mfma_f32_16x16x32_f16 v[48:51], v[182:185], v[190:193], v[48:51]
	v_mfma_f32_16x16x32_f16 v[36:39], v[174:177], v[198:201], v[36:39]
	v_mfma_f32_16x16x32_f16 v[32:35], v[182:185], v[198:201], v[32:35]
	v_mfma_f32_16x16x32_f16 v[20:23], v[174:177], v[206:209], v[20:23]
	v_mfma_f32_16x16x32_f16 v[16:19], v[182:185], v[206:209], v[16:19]
	v_mfma_f32_16x16x32_f16 v[4:7], v[174:177], v[214:217], v[4:7]
	v_mfma_f32_16x16x32_f16 v[0:3], v[182:185], v[214:217], v[0:3]
	v_mfma_f32_16x16x32_f16 v[52:55], v[178:181], v[194:197], v[52:55]
	v_mfma_f32_16x16x32_f16 v[48:51], v[186:189], v[194:197], v[48:51]
	v_mfma_f32_16x16x32_f16 v[36:39], v[178:181], v[202:205], v[36:39]
	v_mfma_f32_16x16x32_f16 v[32:35], v[186:189], v[202:205], v[32:35]
	v_mfma_f32_16x16x32_f16 v[20:23], v[178:181], v[210:213], v[20:23]
	v_mfma_f32_16x16x32_f16 v[16:19], v[186:189], v[210:213], v[16:19]
	v_mfma_f32_16x16x32_f16 v[4:7], v[178:181], v[218:221], v[4:7]
	v_mfma_f32_16x16x32_f16 v[0:3], v[186:189], v[218:221], v[0:3]
	s_barrier
	s_add_i32 s51, s51, 2
	s_add_u32 s22, s22, 0x100
	s_addc_u32 s23, s23, 0
	s_add_u32 s13, s13, 0x100
	s_addc_u32 s15, s15, 0
	s_cmp_gt_u32 s51, 13
